# K-loops: the MFMA block's priority raise is issued before its opening barrier (first instruction after the barrier is the first MFMA)
# speedup vs baseline: 1.0073x; 1.0042x over previous
; #define PG8_STAGE(bufoff, gbase, voff) do { _Pragma("unroll") for (int _i = 0; _i < 2; ++_i) \
;         __builtin_amdgcn_global_load_lds((const unsigned*)((const char*)(gbase) + (voff)[_i]), (PG8_LAS unsigned*)(lds + (bufoff) + ldsw + _i * 8192), 16, 0, 0); } while (0)
; #define PG8_LDA(dst, b, h) do { _Pragma("unroll") for (int m = 0; m < 4; ++m) _Pragma("unroll") for (int k = 0; k < 2; ++k) dst[m][k] = *(const PG8_LAS bf16x8*)(lds + PG8_SA(b, h) + aoff + m * 2048 + k * 1024); } while (0)
; #define PG8_LDB(dst, b, h) do { _Pragma("unroll") for (int n = 0; n < 2; ++n) _Pragma("unroll") for (int k = 0; k < 2; ++k) dst[n][k] = *(const PG8_LAS bf16x8*)(lds + PG8_SB(b, h) + boff + n * 2048 + k * 1024); } while (0)
; #define PG8_MMA(ai, bj, At, Bt) do { __builtin_amdgcn_s_setprio(1); _Pragma("unroll") for (int m = 0; m < 4; ++m) _Pragma("unroll") for (int n = 0; n < 2; ++n) _Pragma("unroll") for (int k = 0; k < 2; ++k) \
;         acc[ai][bj][m][n] = __builtin_amdgcn_mfma_f32_16x16x32_bf16(Bt[n][k], At[m][k], acc[ai][bj][m][n], 0, 0, 0); __builtin_amdgcn_s_setprio(0); } while (0)
; #define PG8_WAIT_V(n) asm volatile("s_waitcnt vmcnt(" #n ")" ::: "memory")
; #define PG8_BAR __builtin_amdgcn_s_barrier()
; template <class Epi, class Sched, bool ALIGN_EPI = false, bool SP2 = false>
; __device__ __forceinline__ void gemm_phase(PG8_LAS unsigned char* lds, const Gemm g, const Sched& S, const Epi& E) {
;     ...
;         for (int t = 0; t < nt; t += 2) {
;             const bool last = (t == nt - 2);
;             const char* a1 = cA + (size_t)(t + 1) * kstep;
;             const char* a2 = last ? nA : cA + (size_t)(t + 2) * kstep; const char* b2 = last ? nB : cB + (size_t)(t + 2) * kstep;
;             const char* a3 = a2 + kstep; const char* b3 = b2 + kstep;
;             if (last && has_next) S.a_ready(nxt);
;             if constexpr (SP2) {
;             PG8_LDB(B0, 0, 0); PG8_LDB(B1, 0, 1); PG8_SCHED; PG8_LDA(At, 0, 0); PG8_STAGE(PG8_SA(1, 1), a1 + hstep, voffA);
;             PG8_WAIT_V(8); PG8_WAIT_L(0); PG8_BAR; PG8_MMA(0, 0, At, B0); PG8_MMA(0, 1, At, B1); PG8_BAR; PG8_SCHED;
;             PG8_LDA(At, 0, 1); PG8_STAGE(PG8_SB(0, 0), b2, voffB); PG8_STAGE(PG8_SB(0, 1), b2 + hstep, voffB); PG8_STAGE(PG8_SA(0, 0), a2, voffA);
;             PG8_WAIT_V(8); PG8_WAIT_L(0); PG8_BAR; PG8_MMA(1, 0, At, B0); PG8_MMA(1, 1, At, B1); PG8_BAR; PG8_SCHED;
.LBB0_36:
	s_add_u32 s18, s58, 0xffe00080
	s_addc_u32 s19, s59, -1
	s_add_i32 s47, 0, 0x10000
	s_cmpk_eq_i32 s46, 0x7c
	s_cselect_b32 s63, s45, s19
	s_cselect_b32 s62, s73, s18
	v_add_u32_e32 v160, s47, v143
	s_cselect_b32 s19, s37, s79
	s_cselect_b32 s18, s84, s78
	s_add_i32 s80, 0, 0x14000
	ds_read_b128 v[156:159], v160
	ds_read_b128 v[164:167], v160 offset:1024
	ds_read_b128 v[168:171], v160 offset:2048
	ds_read_b128 v[172:175], v160 offset:3072
	v_add_u32_e32 v160, s80, v143
	ds_read_b128 v[176:179], v160
	ds_read_b128 v[180:183], v160 offset:1024
	ds_read_b128 v[184:187], v160 offset:2048
	ds_read_b128 v[204:207], v160 offset:3072
	v_lshl_add_u64 v[160:161], s[58:59], 0, v[152:153]
	s_add_i32 m0, s5, 0xc000
	ds_read_b128 v[208:211], v163
	ds_read_b128 v[212:215], v163 offset:1024
	ds_read_b128 v[216:219], v163 offset:2048
	ds_read_b128 v[220:223], v163 offset:3072
	ds_read_b128 v[224:227], v163 offset:4096
	ds_read_b128 v[228:231], v163 offset:5120
	ds_read_b128 v[232:235], v163 offset:6144
	ds_read_b128 v[236:239], v163 offset:7168
	global_load_lds_dwordx4 v[160:161], off
	v_lshl_add_u64 v[160:161], s[58:59], 0, v[154:155]
	s_add_i32 m0, s5, 0xe000
	s_nop 0
	global_load_lds_dwordx4 v[160:161], off
	s_nop 0
	s_waitcnt vmcnt(8)
	s_waitcnt lgkmcnt(0)
	s_setprio 1
	s_barrier
	v_mfma_f32_16x16x32_bf16 v[126:129], v[156:159], v[208:211], v[126:129]
	v_mfma_f32_16x16x32_bf16 v[122:125], v[168:171], v[208:211], v[122:125]
	v_mfma_f32_16x16x32_bf16 v[110:113], v[156:159], v[216:219], v[110:113]
	v_mfma_f32_16x16x32_bf16 v[106:109], v[168:171], v[216:219], v[106:109]
	v_mfma_f32_16x16x32_bf16 v[94:97], v[156:159], v[224:227], v[94:97]
	v_mfma_f32_16x16x32_bf16 v[90:93], v[168:171], v[224:227], v[90:93]
	v_mfma_f32_16x16x32_bf16 v[78:81], v[156:159], v[232:235], v[78:81]
	v_mfma_f32_16x16x32_bf16 v[74:77], v[168:171], v[232:235], v[74:77]
	s_setprio 0
	s_setprio 1
	v_mfma_f32_16x16x32_bf16 v[126:129], v[164:167], v[212:215], v[126:129]
	v_mfma_f32_16x16x32_bf16 v[122:125], v[172:175], v[212:215], v[122:125]
	v_mfma_f32_16x16x32_bf16 v[110:113], v[164:167], v[220:223], v[110:113]
	v_mfma_f32_16x16x32_bf16 v[106:109], v[172:175], v[220:223], v[106:109]
	v_mfma_f32_16x16x32_bf16 v[94:97], v[164:167], v[228:231], v[94:97]
	v_mfma_f32_16x16x32_bf16 v[90:93], v[172:175], v[228:231], v[90:93]
	v_mfma_f32_16x16x32_bf16 v[78:81], v[164:167], v[236:239], v[78:81]
	v_mfma_f32_16x16x32_bf16 v[74:77], v[172:175], v[236:239], v[74:77]
	s_setprio 0
	s_setprio 1
	v_mfma_f32_16x16x32_bf16 v[118:121], v[176:179], v[208:211], v[118:121]
	v_mfma_f32_16x16x32_bf16 v[114:117], v[184:187], v[208:211], v[114:117]
	v_mfma_f32_16x16x32_bf16 v[102:105], v[176:179], v[216:219], v[102:105]
	v_mfma_f32_16x16x32_bf16 v[98:101], v[184:187], v[216:219], v[98:101]
	v_mfma_f32_16x16x32_bf16 v[86:89], v[176:179], v[224:227], v[86:89]
	v_mfma_f32_16x16x32_bf16 v[82:85], v[184:187], v[224:227], v[82:85]
	v_mfma_f32_16x16x32_bf16 v[70:73], v[176:179], v[232:235], v[70:73]
	v_mfma_f32_16x16x32_bf16 v[66:69], v[184:187], v[232:235], v[66:69]
	s_setprio 0
	s_setprio 1
	v_mfma_f32_16x16x32_bf16 v[118:121], v[180:183], v[212:215], v[118:121]
	v_mfma_f32_16x16x32_bf16 v[114:117], v[204:207], v[212:215], v[114:117]
	v_mfma_f32_16x16x32_bf16 v[102:105], v[180:183], v[220:223], v[102:105]
	v_mfma_f32_16x16x32_bf16 v[98:101], v[204:207], v[220:223], v[98:101]
	v_mfma_f32_16x16x32_bf16 v[86:89], v[180:183], v[228:231], v[86:89]
	v_mfma_f32_16x16x32_bf16 v[82:85], v[204:207], v[228:231], v[82:85]
	v_mfma_f32_16x16x32_bf16 v[70:73], v[180:183], v[236:239], v[70:73]
	v_mfma_f32_16x16x32_bf16 v[66:69], v[204:207], v[236:239], v[66:69]
	s_setprio 0
	s_barrier
	s_add_i32 s47, s47, s4
	v_lshl_add_u64 v[160:161], s[18:19], 0, v[148:149]
	s_mov_b32 m0, s47
	ds_read_b128 v[208:211], v163 offset:16384
	ds_read_b128 v[212:215], v163 offset:17408
	ds_read_b128 v[216:219], v163 offset:18432
	ds_read_b128 v[220:223], v163 offset:19456
	ds_read_b128 v[224:227], v163 offset:20480
	ds_read_b128 v[228:231], v163 offset:21504
	ds_read_b128 v[232:235], v163 offset:22528
	ds_read_b128 v[236:239], v163 offset:23552
	global_load_lds_dwordx4 v[160:161], off
	s_add_i32 m0, s47, 0x2000
	s_add_u32 s76, s18, 0x200000
	v_lshl_add_u64 v[240:241], s[18:19], 0, v[144:145]
	s_addc_u32 s77, s19, 0
	s_add_i32 s47, s80, s4
	global_load_lds_dwordx4 v[240:241], off
	v_lshl_add_u64 v[242:243], s[76:77], 0, v[148:149]
	s_mov_b32 m0, s47
	v_lshl_add_u64 v[244:245], s[62:63], 0, v[146:147]
	global_load_lds_dwordx4 v[242:243], off
	v_lshl_add_u64 v[242:243], s[76:77], 0, v[144:145]
	s_add_i32 m0, s47, 0x2000
	s_nop 0
	global_load_lds_dwordx4 v[242:243], off
	v_lshl_add_u64 v[242:243], s[62:63], 0, v[150:151]
	s_mov_b32 m0, s5
	s_nop 0
	global_load_lds_dwordx4 v[242:243], off
	s_mov_b32 m0, s30
	s_nop 0
	global_load_lds_dwordx4 v[244:245], off
	s_waitcnt vmcnt(8)
	s_waitcnt lgkmcnt(0)
	s_setprio 1
	s_barrier
; #define PG8_STAGE(bufoff, gbase, voff) do { _Pragma("unroll") for (int _i = 0; _i < 2; ++_i) \
;         __builtin_amdgcn_global_load_lds((const unsigned*)((const char*)(gbase) + (voff)[_i]), (PG8_LAS unsigned*)(lds + (bufoff) + ldsw + _i * 8192), 16, 0, 0); } while (0)
; #define PG8_LDA(dst, b, h) do { _Pragma("unroll") for (int m = 0; m < 4; ++m) _Pragma("unroll") for (int k = 0; k < 2; ++k) dst[m][k] = *(const PG8_LAS bf16x8*)(lds + PG8_SA(b, h) + aoff + m * 2048 + k * 1024); } while (0)
; #define PG8_LDB(dst, b, h) do { _Pragma("unroll") for (int n = 0; n < 2; ++n) _Pragma("unroll") for (int k = 0; k < 2; ++k) dst[n][k] = *(const PG8_LAS bf16x8*)(lds + PG8_SB(b, h) + boff + n * 2048 + k * 1024); } while (0)
; #define PG8_MMA(ai, bj, At, Bt) do { __builtin_amdgcn_s_setprio(1); _Pragma("unroll") for (int m = 0; m < 4; ++m) _Pragma("unroll") for (int n = 0; n < 2; ++n) _Pragma("unroll") for (int k = 0; k < 2; ++k) \
;         acc[ai][bj][m][n] = __builtin_amdgcn_mfma_f32_16x16x32_bf16(Bt[n][k], At[m][k], acc[ai][bj][m][n], 0, 0, 0); __builtin_amdgcn_s_setprio(0); } while (0)
; #define PG8_WAIT_V(n) asm volatile("s_waitcnt vmcnt(" #n ")" ::: "memory")
; #define PG8_WAIT_L(n) asm volatile("s_waitcnt lgkmcnt(" #n ")" ::: "memory")
; #define PG8_BAR __builtin_amdgcn_s_barrier()
; #define PG8_SCHED __builtin_amdgcn_sched_barrier(0)
; template <class Epi, class Sched, bool ALIGN_EPI = false, bool SP2 = false>
; __device__ __forceinline__ void gemm_phase(PG8_LAS unsigned char* lds, const Gemm g, const Sched& S, const Epi& E) {
;     ...
;             PG8_WAIT_V(8); PG8_WAIT_L(0); PG8_BAR; PG8_MMA(1, 0, At, B0); PG8_MMA(1, 1, At, B1); PG8_BAR; PG8_SCHED;
;             PG8_LDB(B0, 1, 0); PG8_LDB(B1, 1, 1); PG8_SCHED; PG8_LDA(At, 1, 0); PG8_STAGE(PG8_SA(0, 1), a2 + hstep, voffA);
;             PG8_WAIT_V(8); PG8_WAIT_L(0); PG8_BAR; PG8_MMA(0, 0, At, B0); PG8_MMA(0, 1, At, B1); PG8_BAR; PG8_SCHED;
	v_mfma_f32_16x16x32_bf16 v[62:65], v[156:159], v[208:211], v[62:65]
	v_mfma_f32_16x16x32_bf16 v[58:61], v[168:171], v[208:211], v[58:61]
	v_mfma_f32_16x16x32_bf16 v[46:49], v[156:159], v[216:219], v[46:49]
	v_mfma_f32_16x16x32_bf16 v[42:45], v[168:171], v[216:219], v[42:45]
	v_mfma_f32_16x16x32_bf16 v[30:33], v[156:159], v[224:227], v[30:33]
	v_mfma_f32_16x16x32_bf16 v[26:29], v[168:171], v[224:227], v[26:29]
	v_mfma_f32_16x16x32_bf16 v[14:17], v[156:159], v[232:235], v[14:17]
	v_mfma_f32_16x16x32_bf16 v[10:13], v[168:171], v[232:235], v[10:13]
	s_setprio 0
	s_setprio 1
	v_mfma_f32_16x16x32_bf16 v[62:65], v[164:167], v[212:215], v[62:65]
	v_mfma_f32_16x16x32_bf16 v[58:61], v[172:175], v[212:215], v[58:61]
	v_mfma_f32_16x16x32_bf16 v[46:49], v[164:167], v[220:223], v[46:49]
	v_mfma_f32_16x16x32_bf16 v[42:45], v[172:175], v[220:223], v[42:45]
	v_mfma_f32_16x16x32_bf16 v[30:33], v[164:167], v[228:231], v[30:33]
	v_mfma_f32_16x16x32_bf16 v[26:29], v[172:175], v[228:231], v[26:29]
	v_mfma_f32_16x16x32_bf16 v[14:17], v[164:167], v[236:239], v[14:17]
	v_mfma_f32_16x16x32_bf16 v[10:13], v[172:175], v[236:239], v[10:13]
	s_setprio 0
	s_setprio 1
	v_mfma_f32_16x16x32_bf16 v[54:57], v[176:179], v[208:211], v[54:57]
	v_mfma_f32_16x16x32_bf16 v[50:53], v[184:187], v[208:211], v[50:53]
	v_mfma_f32_16x16x32_bf16 v[38:41], v[176:179], v[216:219], v[38:41]
	v_mfma_f32_16x16x32_bf16 v[34:37], v[184:187], v[216:219], v[34:37]
	v_mfma_f32_16x16x32_bf16 v[22:25], v[176:179], v[224:227], v[22:25]
	v_mfma_f32_16x16x32_bf16 v[18:21], v[184:187], v[224:227], v[18:21]
	v_mfma_f32_16x16x32_bf16 v[6:9], v[176:179], v[232:235], v[6:9]
	v_mfma_f32_16x16x32_bf16 v[2:5], v[184:187], v[232:235], v[2:5]
	s_setprio 0
	s_setprio 1
	v_mfma_f32_16x16x32_bf16 v[54:57], v[180:183], v[212:215], v[54:57]
	v_mfma_f32_16x16x32_bf16 v[50:53], v[204:207], v[212:215], v[50:53]
	v_mfma_f32_16x16x32_bf16 v[38:41], v[180:183], v[220:223], v[38:41]
	v_mfma_f32_16x16x32_bf16 v[34:37], v[204:207], v[220:223], v[34:37]
	v_mfma_f32_16x16x32_bf16 v[22:25], v[180:183], v[228:231], v[22:25]
	v_mfma_f32_16x16x32_bf16 v[18:21], v[204:207], v[228:231], v[18:21]
	v_mfma_f32_16x16x32_bf16 v[6:9], v[180:183], v[236:239], v[6:9]
	v_mfma_f32_16x16x32_bf16 v[2:5], v[204:207], v[236:239], v[2:5]
	s_setprio 0
	s_barrier
	s_add_i32 s47, 0, 0x18000
	s_add_i32 s76, 0, 0x1c000
	v_add_u32_e32 v172, s47, v143
	v_add_u32_e32 v203, s76, v143
	ds_read_b128 v[156:159], v172
	ds_read_b128 v[164:167], v172 offset:1024
	ds_read_b128 v[168:171], v172 offset:2048
	ds_read_b128 v[172:175], v172 offset:3072
	ds_read_b128 v[176:179], v203
	ds_read_b128 v[180:183], v203 offset:1024
	ds_read_b128 v[184:187], v203 offset:2048
	ds_read_b128 v[204:207], v203 offset:3072
	s_add_u32 s62, s62, 0x200000
	s_addc_u32 s63, s63, 0
	s_mov_b32 m0, s57
	v_lshl_add_u64 v[246:247], s[62:63], 0, v[150:151]
	ds_read_b128 v[208:211], v163 offset:32768
	ds_read_b128 v[212:215], v163 offset:33792
	ds_read_b128 v[216:219], v163 offset:34816
	ds_read_b128 v[220:223], v163 offset:35840
	ds_read_b128 v[224:227], v163 offset:36864
	ds_read_b128 v[228:231], v163 offset:37888
	ds_read_b128 v[232:235], v163 offset:38912
	ds_read_b128 v[236:239], v163 offset:39936
	global_load_lds_dwordx4 v[246:247], off
	v_lshl_add_u64 v[246:247], s[62:63], 0, v[146:147]
	s_mov_b32 m0, s67
	s_nop 0
	global_load_lds_dwordx4 v[246:247], off
	s_waitcnt vmcnt(8)
	s_waitcnt lgkmcnt(0)
	s_setprio 1
	s_barrier
	v_mfma_f32_16x16x32_bf16 v[126:129], v[156:159], v[208:211], v[126:129]
	v_mfma_f32_16x16x32_bf16 v[122:125], v[168:171], v[208:211], v[122:125]
	v_mfma_f32_16x16x32_bf16 v[110:113], v[156:159], v[216:219], v[110:113]
	v_mfma_f32_16x16x32_bf16 v[106:109], v[168:171], v[216:219], v[106:109]
	v_mfma_f32_16x16x32_bf16 v[94:97], v[156:159], v[224:227], v[94:97]
	v_mfma_f32_16x16x32_bf16 v[90:93], v[168:171], v[224:227], v[90:93]
	v_mfma_f32_16x16x32_bf16 v[78:81], v[156:159], v[232:235], v[78:81]
	v_mfma_f32_16x16x32_bf16 v[74:77], v[168:171], v[232:235], v[74:77]
	s_setprio 0
	s_setprio 1
	v_mfma_f32_16x16x32_bf16 v[126:129], v[164:167], v[212:215], v[126:129]
	v_mfma_f32_16x16x32_bf16 v[122:125], v[172:175], v[212:215], v[122:125]
	v_mfma_f32_16x16x32_bf16 v[110:113], v[164:167], v[220:223], v[110:113]
	v_mfma_f32_16x16x32_bf16 v[106:109], v[172:175], v[220:223], v[106:109]
	v_mfma_f32_16x16x32_bf16 v[94:97], v[164:167], v[228:231], v[94:97]
	v_mfma_f32_16x16x32_bf16 v[90:93], v[172:175], v[228:231], v[90:93]
	v_mfma_f32_16x16x32_bf16 v[78:81], v[164:167], v[236:239], v[78:81]
	v_mfma_f32_16x16x32_bf16 v[74:77], v[172:175], v[236:239], v[74:77]
	s_setprio 0
	s_setprio 1
	v_mfma_f32_16x16x32_bf16 v[118:121], v[176:179], v[208:211], v[118:121]
	v_mfma_f32_16x16x32_bf16 v[114:117], v[184:187], v[208:211], v[114:117]
	v_mfma_f32_16x16x32_bf16 v[102:105], v[176:179], v[216:219], v[102:105]
	v_mfma_f32_16x16x32_bf16 v[98:101], v[184:187], v[216:219], v[98:101]
	v_mfma_f32_16x16x32_bf16 v[86:89], v[176:179], v[224:227], v[86:89]
	v_mfma_f32_16x16x32_bf16 v[82:85], v[184:187], v[224:227], v[82:85]
	v_mfma_f32_16x16x32_bf16 v[70:73], v[176:179], v[232:235], v[70:73]
	v_mfma_f32_16x16x32_bf16 v[66:69], v[184:187], v[232:235], v[66:69]
	s_setprio 0
	s_setprio 1
	v_mfma_f32_16x16x32_bf16 v[118:121], v[180:183], v[212:215], v[118:121]
	v_mfma_f32_16x16x32_bf16 v[114:117], v[204:207], v[212:215], v[114:117]
	v_mfma_f32_16x16x32_bf16 v[102:105], v[180:183], v[220:223], v[102:105]
	v_mfma_f32_16x16x32_bf16 v[98:101], v[204:207], v[220:223], v[98:101]
	v_mfma_f32_16x16x32_bf16 v[86:89], v[180:183], v[228:231], v[86:89]
	v_mfma_f32_16x16x32_bf16 v[82:85], v[204:207], v[228:231], v[82:85]
	v_mfma_f32_16x16x32_bf16 v[70:73], v[180:183], v[236:239], v[70:73]
	v_mfma_f32_16x16x32_bf16 v[66:69], v[204:207], v[236:239], v[66:69]
	s_setprio 0
	s_barrier
; #define PG8_STAGE(bufoff, gbase, voff) do { _Pragma("unroll") for (int _i = 0; _i < 2; ++_i) \
;         __builtin_amdgcn_global_load_lds((const unsigned*)((const char*)(gbase) + (voff)[_i]), (PG8_LAS unsigned*)(lds + (bufoff) + ldsw + _i * 8192), 16, 0, 0); } while (0)
; #define PG8_LDA(dst, b, h) do { _Pragma("unroll") for (int m = 0; m < 4; ++m) _Pragma("unroll") for (int k = 0; k < 2; ++k) dst[m][k] = *(const PG8_LAS bf16x8*)(lds + PG8_SA(b, h) + aoff + m * 2048 + k * 1024); } while (0)
; #define PG8_WAIT_V(n) asm volatile("s_waitcnt vmcnt(" #n ")" ::: "memory")
; template <class Epi, class Sched, bool ALIGN_EPI = false, bool SP2 = false>
; __device__ __forceinline__ void gemm_phase(PG8_LAS unsigned char* lds, const Gemm g, const Sched& S, const Epi& E) {
;     ...
;             PG8_LDA(At, 1, 1); PG8_STAGE(PG8_SB(1, 0), b3, voffB); PG8_STAGE(PG8_SB(1, 1), b3 + hstep, voffB); PG8_STAGE(PG8_SA(1, 0), a3, voffA);
;             PG8_WAIT_V(8); PG8_WAIT_L(0); PG8_BAR; PG8_MMA(1, 0, At, B0); PG8_MMA(1, 1, At, B1); PG8_BAR; PG8_SCHED;
;             } else {
;             PG8_LDB(B0, 0, 0); PG8_SCHED; PG8_LDA(At, 0, 0); PG8_STAGE(PG8_SA(1, 1), a1 + hstep, voffA);
;             PG8_WAIT_L(8); PG8_BAR; PG8_WAIT_L(0); PG8_MMA(0, 0, At, B0); PG8_BAR; PG8_SCHED;
;             PG8_LDB(B1, 0, 1); PG8_STAGE(PG8_SB(0, 0), b2, voffB);
;             PG8_BAR; PG8_WAIT_L(0); PG8_MMA(0, 1, At, B1); PG8_BAR;
;             PG8_LDA(At, 0, 1); PG8_STAGE(PG8_SA(0, 0), a2, voffA);
;             PG8_BAR; PG8_WAIT_L(0); PG8_MMA(1, 0, At, B0); PG8_BAR; PG8_SCHED;
;             PG8_STAGE(PG8_SB(0, 1), b2 + hstep, voffB);
;             PG8_WAIT_V(6); PG8_BAR; PG8_MMA(1, 1, At, B1); PG8_BAR;
;             PG8_LDB(B0, 1, 0); PG8_SCHED; PG8_LDA(At, 1, 0); PG8_STAGE(PG8_SA(0, 1), a2 + hstep, voffA);
;             PG8_WAIT_L(8); PG8_BAR; PG8_WAIT_L(0); PG8_MMA(0, 0, At, B0); PG8_BAR; PG8_SCHED;
;             PG8_LDB(B1, 1, 1); PG8_STAGE(PG8_SB(1, 0), b3, voffB);
;             PG8_BAR; PG8_WAIT_L(0); PG8_MMA(0, 1, At, B1); PG8_BAR;
;             PG8_LDA(At, 1, 1); PG8_STAGE(PG8_SA(1, 0), a3, voffA);
;             PG8_BAR; PG8_WAIT_L(0); PG8_MMA(1, 0, At, B0); PG8_BAR; PG8_SCHED;
;             PG8_STAGE(PG8_SB(1, 1), b3 + hstep, voffB);
;             PG8_WAIT_V(6); PG8_BAR; PG8_MMA(1, 1, At, B1); PG8_BAR;
;             }
;         }
;         if constexpr (ALIGN_EPI) { if (wr == 0) PG8_BAR; }
	s_add_i32 s47, s47, s4
	v_lshl_add_u64 v[160:161], v[160:161], 0, s[68:69]
	s_mov_b32 m0, s47
	ds_read_b128 v[208:211], v163 offset:49152
	ds_read_b128 v[212:215], v163 offset:50176
	ds_read_b128 v[216:219], v163 offset:51200
	ds_read_b128 v[220:223], v163 offset:52224
	ds_read_b128 v[224:227], v163 offset:53248
	ds_read_b128 v[228:231], v163 offset:54272
	ds_read_b128 v[232:235], v163 offset:55296
	ds_read_b128 v[236:239], v163 offset:56320
	global_load_lds_dwordx4 v[160:161], off
	s_add_i32 m0, s47, 0x2000
	s_add_u32 s18, s18, 0x200080
	v_lshl_add_u64 v[160:161], v[240:241], 0, s[68:69]
	s_addc_u32 s19, s19, 0
	s_add_i32 s47, s76, s4
	global_load_lds_dwordx4 v[160:161], off
	v_lshl_add_u64 v[160:161], s[18:19], 0, v[148:149]
	s_mov_b32 m0, s47
	s_nop 0
	global_load_lds_dwordx4 v[160:161], off
	v_lshl_add_u64 v[160:161], s[18:19], 0, v[144:145]
	s_add_i32 m0, s47, 0x2000
	s_nop 0
	global_load_lds_dwordx4 v[160:161], off
	v_lshl_add_u64 v[160:161], v[242:243], 0, s[68:69]
	s_mov_b32 m0, s1
	s_nop 0
	global_load_lds_dwordx4 v[160:161], off
	v_lshl_add_u64 v[160:161], v[244:245], 0, s[68:69]
	s_mov_b32 m0, s60
	s_nop 0
	global_load_lds_dwordx4 v[160:161], off
	s_nop 0
	s_waitcnt vmcnt(8)
	s_waitcnt lgkmcnt(0)
	s_setprio 1
	s_barrier
	v_mfma_f32_16x16x32_bf16 v[62:65], v[156:159], v[208:211], v[62:65]
	v_mfma_f32_16x16x32_bf16 v[58:61], v[168:171], v[208:211], v[58:61]
	v_mfma_f32_16x16x32_bf16 v[46:49], v[156:159], v[216:219], v[46:49]
	v_mfma_f32_16x16x32_bf16 v[42:45], v[168:171], v[216:219], v[42:45]
	v_mfma_f32_16x16x32_bf16 v[30:33], v[156:159], v[224:227], v[30:33]
	v_mfma_f32_16x16x32_bf16 v[26:29], v[168:171], v[224:227], v[26:29]
	v_mfma_f32_16x16x32_bf16 v[14:17], v[156:159], v[232:235], v[14:17]
	v_mfma_f32_16x16x32_bf16 v[10:13], v[168:171], v[232:235], v[10:13]
	s_setprio 0
	s_setprio 1
	v_mfma_f32_16x16x32_bf16 v[62:65], v[164:167], v[212:215], v[62:65]
	v_mfma_f32_16x16x32_bf16 v[58:61], v[172:175], v[212:215], v[58:61]
	v_mfma_f32_16x16x32_bf16 v[46:49], v[164:167], v[220:223], v[46:49]
	v_mfma_f32_16x16x32_bf16 v[42:45], v[172:175], v[220:223], v[42:45]
	v_mfma_f32_16x16x32_bf16 v[30:33], v[164:167], v[228:231], v[30:33]
	v_mfma_f32_16x16x32_bf16 v[26:29], v[172:175], v[228:231], v[26:29]
	v_mfma_f32_16x16x32_bf16 v[14:17], v[164:167], v[236:239], v[14:17]
	v_mfma_f32_16x16x32_bf16 v[10:13], v[172:175], v[236:239], v[10:13]
	s_setprio 0
	s_setprio 1
	v_mfma_f32_16x16x32_bf16 v[54:57], v[176:179], v[208:211], v[54:57]
	v_mfma_f32_16x16x32_bf16 v[50:53], v[184:187], v[208:211], v[50:53]
	v_mfma_f32_16x16x32_bf16 v[38:41], v[176:179], v[216:219], v[38:41]
	v_mfma_f32_16x16x32_bf16 v[34:37], v[184:187], v[216:219], v[34:37]
	v_mfma_f32_16x16x32_bf16 v[22:25], v[176:179], v[224:227], v[22:25]
	v_mfma_f32_16x16x32_bf16 v[18:21], v[184:187], v[224:227], v[18:21]
	v_mfma_f32_16x16x32_bf16 v[6:9], v[176:179], v[232:235], v[6:9]
	v_mfma_f32_16x16x32_bf16 v[2:5], v[184:187], v[232:235], v[2:5]
	s_setprio 0
	s_setprio 1
	v_mfma_f32_16x16x32_bf16 v[54:57], v[180:183], v[212:215], v[54:57]
	v_mfma_f32_16x16x32_bf16 v[50:53], v[204:207], v[212:215], v[50:53]
	v_mfma_f32_16x16x32_bf16 v[38:41], v[180:183], v[220:223], v[38:41]
	v_mfma_f32_16x16x32_bf16 v[34:37], v[204:207], v[220:223], v[34:37]
	v_mfma_f32_16x16x32_bf16 v[22:25], v[180:183], v[228:231], v[22:25]
	v_mfma_f32_16x16x32_bf16 v[18:21], v[204:207], v[228:231], v[18:21]
	v_mfma_f32_16x16x32_bf16 v[6:9], v[180:183], v[236:239], v[6:9]
	v_mfma_f32_16x16x32_bf16 v[2:5], v[204:207], v[236:239], v[2:5]
	s_setprio 0
	s_barrier
	s_add_i32 s46, s46, 2
	s_add_u32 s58, s58, 0x100
	s_addc_u32 s59, s59, 0
	s_add_u32 s78, s78, 0x100
	s_addc_u32 s79, s79, 0
	s_cmpk_gt_u32 s46, 0x7d
	s_cbranch_scc0 .LBB0_36
	s_and_b64 vcc, exec, s[12:13]
	s_cbranch_vccz .LBB0_39
	s_barrier

; #define PG8_STAGE(bufoff, gbase, voff) do { _Pragma("unroll") for (int _i = 0; _i < 2; ++_i) \
;         __builtin_amdgcn_global_load_lds((const unsigned*)((const char*)(gbase) + (voff)[_i]), (PG8_LAS unsigned*)(lds + (bufoff) + ldsw + _i * 8192), 16, 0, 0); } while (0)
; #define PG8_LDA(dst, b, h) do { _Pragma("unroll") for (int m = 0; m < 4; ++m) _Pragma("unroll") for (int k = 0; k < 2; ++k) dst[m][k] = *(const PG8_LAS bf16x8*)(lds + PG8_SA(b, h) + aoff + m * 2048 + k * 1024); } while (0)
; #define PG8_LDB(dst, b, h) do { _Pragma("unroll") for (int n = 0; n < 2; ++n) _Pragma("unroll") for (int k = 0; k < 2; ++k) dst[n][k] = *(const PG8_LAS bf16x8*)(lds + PG8_SB(b, h) + boff + n * 2048 + k * 1024); } while (0)
; #define PG8_WAIT_V(n) asm volatile("s_waitcnt vmcnt(" #n ")" ::: "memory")
; #define PG8_WAIT_L(n) asm volatile("s_waitcnt lgkmcnt(" #n ")" ::: "memory")
; #define PG8_BAR __builtin_amdgcn_s_barrier()
; #define PG8_SCHED __builtin_amdgcn_sched_barrier(0)
; template <class Epi, class Sched, bool ALIGN_EPI = false, bool SP2 = false>
; __device__ __forceinline__ void gemm_phase(PG8_LAS unsigned char* lds, const Gemm g, const Sched& S, const Epi& E) {
;     ...
;         const char* nA = has_next ? (const char*)g.A + (size_t)nxt.pm * tstep : cA; const char* nB = has_next ? (const char*)g.Bt + (size_t)nxt.pn * tstep : cB;
;         for (int t = 0; t < nt; t += 2) {
;             const bool last = (t == nt - 2);
;             const char* a1 = cA + (size_t)(t + 1) * kstep;
;             const char* a2 = last ? nA : cA + (size_t)(t + 2) * kstep; const char* b2 = last ? nB : cB + (size_t)(t + 2) * kstep;
;             const char* a3 = a2 + kstep; const char* b3 = b2 + kstep;
;             if (last && has_next) S.a_ready(nxt);
;             if constexpr (SP2) {
;             PG8_LDB(B0, 0, 0); PG8_LDB(B1, 0, 1); PG8_SCHED; PG8_LDA(At, 0, 0); PG8_STAGE(PG8_SA(1, 1), a1 + hstep, voffA);
;             PG8_WAIT_V(8); PG8_WAIT_L(0); PG8_BAR; PG8_MMA(0, 0, At, B0); PG8_MMA(0, 1, At, B1); PG8_BAR; PG8_SCHED;
;             PG8_LDA(At, 0, 1); PG8_STAGE(PG8_SB(0, 0), b2, voffB); PG8_STAGE(PG8_SB(0, 1), b2 + hstep, voffB); PG8_STAGE(PG8_SA(0, 0), a2, voffA);
;             PG8_WAIT_V(8); PG8_WAIT_L(0); PG8_BAR; PG8_MMA(1, 0, At, B0); PG8_MMA(1, 1, At, B1); PG8_BAR; PG8_SCHED;
.LBB0_76:
	s_add_u32 s18, s0, 0xfff80080
	s_addc_u32 s19, s1, -1
	s_add_i32 s47, 0, 0x10000
	s_cmp_eq_u32 s46, 28
	s_cselect_b32 s59, s60, s19
	s_cselect_b32 s58, s73, s18
	v_add_u32_e32 v158, s47, v143
	s_cselect_b32 s19, s45, s79
	s_cselect_b32 s18, s84, s78
	s_add_i32 s80, 0, 0x14000
	ds_read_b128 v[162:165], v158
	ds_read_b128 v[166:169], v158 offset:1024
	ds_read_b128 v[170:173], v158 offset:2048
	ds_read_b128 v[174:177], v158 offset:3072
	v_add_u32_e32 v158, s80, v143
	ds_read_b128 v[178:181], v158
	ds_read_b128 v[182:185], v158 offset:1024
	ds_read_b128 v[204:207], v158 offset:2048
	ds_read_b128 v[208:211], v158 offset:3072
	v_lshl_add_u64 v[158:159], s[0:1], 0, v[154:155]
	s_add_i32 m0, s62, 0xc000
	ds_read_b128 v[212:215], v161
	ds_read_b128 v[216:219], v161 offset:1024
	ds_read_b128 v[220:223], v161 offset:2048
	ds_read_b128 v[224:227], v161 offset:3072
	ds_read_b128 v[228:231], v161 offset:4096
	ds_read_b128 v[232:235], v161 offset:5120
	ds_read_b128 v[236:239], v161 offset:6144
	ds_read_b128 v[240:243], v161 offset:7168
	global_load_lds_dwordx4 v[158:159], off
	v_lshl_add_u64 v[158:159], s[0:1], 0, v[156:157]
	s_add_i32 m0, s62, 0xe000
	s_nop 0
	global_load_lds_dwordx4 v[158:159], off
	s_nop 0
	s_waitcnt vmcnt(8)
	s_waitcnt lgkmcnt(0)
	s_setprio 1
	s_barrier
	v_mfma_f32_16x16x32_bf16 v[126:129], v[162:165], v[212:215], v[126:129]
	v_mfma_f32_16x16x32_bf16 v[122:125], v[170:173], v[212:215], v[122:125]
	v_mfma_f32_16x16x32_bf16 v[110:113], v[162:165], v[220:223], v[110:113]
	v_mfma_f32_16x16x32_bf16 v[106:109], v[170:173], v[220:223], v[106:109]
	v_mfma_f32_16x16x32_bf16 v[94:97], v[162:165], v[228:231], v[94:97]
	v_mfma_f32_16x16x32_bf16 v[90:93], v[170:173], v[228:231], v[90:93]
	v_mfma_f32_16x16x32_bf16 v[78:81], v[162:165], v[236:239], v[78:81]
	v_mfma_f32_16x16x32_bf16 v[74:77], v[170:173], v[236:239], v[74:77]
	s_setprio 0
	s_setprio 1
	v_mfma_f32_16x16x32_bf16 v[126:129], v[166:169], v[216:219], v[126:129]
	v_mfma_f32_16x16x32_bf16 v[122:125], v[174:177], v[216:219], v[122:125]
	v_mfma_f32_16x16x32_bf16 v[110:113], v[166:169], v[224:227], v[110:113]
	v_mfma_f32_16x16x32_bf16 v[106:109], v[174:177], v[224:227], v[106:109]
	v_mfma_f32_16x16x32_bf16 v[94:97], v[166:169], v[232:235], v[94:97]
	v_mfma_f32_16x16x32_bf16 v[90:93], v[174:177], v[232:235], v[90:93]
	v_mfma_f32_16x16x32_bf16 v[78:81], v[166:169], v[240:243], v[78:81]
	v_mfma_f32_16x16x32_bf16 v[74:77], v[174:177], v[240:243], v[74:77]
	s_setprio 0
	s_setprio 1
	v_mfma_f32_16x16x32_bf16 v[118:121], v[178:181], v[212:215], v[118:121]
	v_mfma_f32_16x16x32_bf16 v[114:117], v[204:207], v[212:215], v[114:117]
	v_mfma_f32_16x16x32_bf16 v[102:105], v[178:181], v[220:223], v[102:105]
	v_mfma_f32_16x16x32_bf16 v[98:101], v[204:207], v[220:223], v[98:101]
	v_mfma_f32_16x16x32_bf16 v[86:89], v[178:181], v[228:231], v[86:89]
	v_mfma_f32_16x16x32_bf16 v[82:85], v[204:207], v[228:231], v[82:85]
	v_mfma_f32_16x16x32_bf16 v[70:73], v[178:181], v[236:239], v[70:73]
	v_mfma_f32_16x16x32_bf16 v[66:69], v[204:207], v[236:239], v[66:69]
	s_setprio 0
	s_setprio 1
	v_mfma_f32_16x16x32_bf16 v[118:121], v[182:185], v[216:219], v[118:121]
	v_mfma_f32_16x16x32_bf16 v[114:117], v[208:211], v[216:219], v[114:117]
	v_mfma_f32_16x16x32_bf16 v[102:105], v[182:185], v[224:227], v[102:105]
	v_mfma_f32_16x16x32_bf16 v[98:101], v[208:211], v[224:227], v[98:101]
	v_mfma_f32_16x16x32_bf16 v[86:89], v[182:185], v[232:235], v[86:89]
	v_mfma_f32_16x16x32_bf16 v[82:85], v[208:211], v[232:235], v[82:85]
	v_mfma_f32_16x16x32_bf16 v[70:73], v[182:185], v[240:243], v[70:73]
	v_mfma_f32_16x16x32_bf16 v[66:69], v[208:211], v[240:243], v[66:69]
	s_setprio 0
	s_barrier
	s_add_i32 s47, s47, s54
	v_lshl_add_u64 v[158:159], s[18:19], 0, v[148:149]
	s_mov_b32 m0, s47
	ds_read_b128 v[212:215], v161 offset:16384
	ds_read_b128 v[216:219], v161 offset:17408
	ds_read_b128 v[220:223], v161 offset:18432
	ds_read_b128 v[224:227], v161 offset:19456
	ds_read_b128 v[228:231], v161 offset:20480
	ds_read_b128 v[232:235], v161 offset:21504
	ds_read_b128 v[236:239], v161 offset:22528
	ds_read_b128 v[240:243], v161 offset:23552
	global_load_lds_dwordx4 v[158:159], off
	s_add_i32 m0, s47, 0x2000
	s_add_u32 s76, s18, 0x80000
	v_lshl_add_u64 v[186:187], s[18:19], 0, v[144:145]
	s_addc_u32 s77, s19, 0
	s_add_i32 s47, s80, s54
	global_load_lds_dwordx4 v[186:187], off
	v_lshl_add_u64 v[244:245], s[76:77], 0, v[148:149]
	s_mov_b32 m0, s47
	v_lshl_add_u64 v[246:247], s[58:59], 0, v[146:147]
	global_load_lds_dwordx4 v[244:245], off
	v_lshl_add_u64 v[244:245], s[76:77], 0, v[144:145]
	s_add_i32 m0, s47, 0x2000
	s_nop 0
	global_load_lds_dwordx4 v[244:245], off
	v_lshl_add_u64 v[244:245], s[58:59], 0, v[150:151]
	s_mov_b32 m0, s62
	s_nop 0
	global_load_lds_dwordx4 v[244:245], off
	s_mov_b32 m0, s63
	s_nop 0
	global_load_lds_dwordx4 v[246:247], off
	s_waitcnt vmcnt(8)
	s_waitcnt lgkmcnt(0)
	s_setprio 1
	s_barrier
; #define PG8_STAGE(bufoff, gbase, voff) do { _Pragma("unroll") for (int _i = 0; _i < 2; ++_i) \
;         __builtin_amdgcn_global_load_lds((const unsigned*)((const char*)(gbase) + (voff)[_i]), (PG8_LAS unsigned*)(lds + (bufoff) + ldsw + _i * 8192), 16, 0, 0); } while (0)
; #define PG8_LDA(dst, b, h) do { _Pragma("unroll") for (int m = 0; m < 4; ++m) _Pragma("unroll") for (int k = 0; k < 2; ++k) dst[m][k] = *(const PG8_LAS bf16x8*)(lds + PG8_SA(b, h) + aoff + m * 2048 + k * 1024); } while (0)
; #define PG8_LDB(dst, b, h) do { _Pragma("unroll") for (int n = 0; n < 2; ++n) _Pragma("unroll") for (int k = 0; k < 2; ++k) dst[n][k] = *(const PG8_LAS bf16x8*)(lds + PG8_SB(b, h) + boff + n * 2048 + k * 1024); } while (0)
; #define PG8_MMA(ai, bj, At, Bt) do { __builtin_amdgcn_s_setprio(1); _Pragma("unroll") for (int m = 0; m < 4; ++m) _Pragma("unroll") for (int n = 0; n < 2; ++n) _Pragma("unroll") for (int k = 0; k < 2; ++k) \
;         acc[ai][bj][m][n] = __builtin_amdgcn_mfma_f32_16x16x32_bf16(Bt[n][k], At[m][k], acc[ai][bj][m][n], 0, 0, 0); __builtin_amdgcn_s_setprio(0); } while (0)
; #define PG8_WAIT_V(n) asm volatile("s_waitcnt vmcnt(" #n ")" ::: "memory")
; #define PG8_WAIT_L(n) asm volatile("s_waitcnt lgkmcnt(" #n ")" ::: "memory")
; #define PG8_BAR __builtin_amdgcn_s_barrier()
; #define PG8_SCHED __builtin_amdgcn_sched_barrier(0)
; template <class Epi, class Sched, bool ALIGN_EPI = false, bool SP2 = false>
; __device__ __forceinline__ void gemm_phase(PG8_LAS unsigned char* lds, const Gemm g, const Sched& S, const Epi& E) {
;     ...
;             PG8_WAIT_V(8); PG8_WAIT_L(0); PG8_BAR; PG8_MMA(1, 0, At, B0); PG8_MMA(1, 1, At, B1); PG8_BAR; PG8_SCHED;
;             PG8_LDB(B0, 1, 0); PG8_LDB(B1, 1, 1); PG8_SCHED; PG8_LDA(At, 1, 0); PG8_STAGE(PG8_SA(0, 1), a2 + hstep, voffA);
;             PG8_WAIT_V(8); PG8_WAIT_L(0); PG8_BAR; PG8_MMA(0, 0, At, B0); PG8_MMA(0, 1, At, B1); PG8_BAR; PG8_SCHED;
	v_mfma_f32_16x16x32_bf16 v[62:65], v[162:165], v[212:215], v[62:65]
	v_mfma_f32_16x16x32_bf16 v[58:61], v[170:173], v[212:215], v[58:61]
	v_mfma_f32_16x16x32_bf16 v[46:49], v[162:165], v[220:223], v[46:49]
	v_mfma_f32_16x16x32_bf16 v[42:45], v[170:173], v[220:223], v[42:45]
	v_mfma_f32_16x16x32_bf16 v[30:33], v[162:165], v[228:231], v[30:33]
	v_mfma_f32_16x16x32_bf16 v[26:29], v[170:173], v[228:231], v[26:29]
	v_mfma_f32_16x16x32_bf16 v[14:17], v[162:165], v[236:239], v[14:17]
	v_mfma_f32_16x16x32_bf16 v[10:13], v[170:173], v[236:239], v[10:13]
	s_setprio 0
	s_setprio 1
	v_mfma_f32_16x16x32_bf16 v[62:65], v[166:169], v[216:219], v[62:65]
	v_mfma_f32_16x16x32_bf16 v[58:61], v[174:177], v[216:219], v[58:61]
	v_mfma_f32_16x16x32_bf16 v[46:49], v[166:169], v[224:227], v[46:49]
	v_mfma_f32_16x16x32_bf16 v[42:45], v[174:177], v[224:227], v[42:45]
	v_mfma_f32_16x16x32_bf16 v[30:33], v[166:169], v[232:235], v[30:33]
	v_mfma_f32_16x16x32_bf16 v[26:29], v[174:177], v[232:235], v[26:29]
	v_mfma_f32_16x16x32_bf16 v[14:17], v[166:169], v[240:243], v[14:17]
	v_mfma_f32_16x16x32_bf16 v[10:13], v[174:177], v[240:243], v[10:13]
	s_setprio 0
	s_setprio 1
	v_mfma_f32_16x16x32_bf16 v[54:57], v[178:181], v[212:215], v[54:57]
	v_mfma_f32_16x16x32_bf16 v[50:53], v[204:207], v[212:215], v[50:53]
	v_mfma_f32_16x16x32_bf16 v[38:41], v[178:181], v[220:223], v[38:41]
	v_mfma_f32_16x16x32_bf16 v[34:37], v[204:207], v[220:223], v[34:37]
	v_mfma_f32_16x16x32_bf16 v[22:25], v[178:181], v[228:231], v[22:25]
	v_mfma_f32_16x16x32_bf16 v[18:21], v[204:207], v[228:231], v[18:21]
	v_mfma_f32_16x16x32_bf16 v[6:9], v[178:181], v[236:239], v[6:9]
	v_mfma_f32_16x16x32_bf16 v[2:5], v[204:207], v[236:239], v[2:5]
	s_setprio 0
	s_setprio 1
	v_mfma_f32_16x16x32_bf16 v[54:57], v[182:185], v[216:219], v[54:57]
	v_mfma_f32_16x16x32_bf16 v[50:53], v[208:211], v[216:219], v[50:53]
	v_mfma_f32_16x16x32_bf16 v[38:41], v[182:185], v[224:227], v[38:41]
	v_mfma_f32_16x16x32_bf16 v[34:37], v[208:211], v[224:227], v[34:37]
	v_mfma_f32_16x16x32_bf16 v[22:25], v[182:185], v[232:235], v[22:25]
	v_mfma_f32_16x16x32_bf16 v[18:21], v[208:211], v[232:235], v[18:21]
	v_mfma_f32_16x16x32_bf16 v[6:9], v[182:185], v[240:243], v[6:9]
	v_mfma_f32_16x16x32_bf16 v[2:5], v[208:211], v[240:243], v[2:5]
	s_setprio 0
	s_barrier
	s_add_i32 s47, 0, 0x18000
	s_add_i32 s76, 0, 0x1c000
	v_add_u32_e32 v174, s47, v143
	v_add_u32_e32 v203, s76, v143
	ds_read_b128 v[162:165], v174
	ds_read_b128 v[166:169], v174 offset:1024
	ds_read_b128 v[170:173], v174 offset:2048
	ds_read_b128 v[174:177], v174 offset:3072
	ds_read_b128 v[178:181], v203
	ds_read_b128 v[182:185], v203 offset:1024
	ds_read_b128 v[204:207], v203 offset:2048
	ds_read_b128 v[208:211], v203 offset:3072
	s_add_u32 s58, s58, 0x80000
	s_addc_u32 s59, s59, 0
	s_mov_b32 m0, s67
	v_lshl_add_u64 v[248:249], s[58:59], 0, v[150:151]
	ds_read_b128 v[212:215], v161 offset:32768
	ds_read_b128 v[216:219], v161 offset:33792
	ds_read_b128 v[220:223], v161 offset:34816
	ds_read_b128 v[224:227], v161 offset:35840
	ds_read_b128 v[228:231], v161 offset:36864
	ds_read_b128 v[232:235], v161 offset:37888
	ds_read_b128 v[236:239], v161 offset:38912
	ds_read_b128 v[240:243], v161 offset:39936
	global_load_lds_dwordx4 v[248:249], off
	v_lshl_add_u64 v[248:249], s[58:59], 0, v[146:147]
	s_mov_b32 m0, s4
	s_nop 0
	global_load_lds_dwordx4 v[248:249], off
	s_waitcnt vmcnt(8)
	s_waitcnt lgkmcnt(0)
	s_setprio 1
	s_barrier
	v_mfma_f32_16x16x32_bf16 v[126:129], v[162:165], v[212:215], v[126:129]
	v_mfma_f32_16x16x32_bf16 v[122:125], v[170:173], v[212:215], v[122:125]
	v_mfma_f32_16x16x32_bf16 v[110:113], v[162:165], v[220:223], v[110:113]
	v_mfma_f32_16x16x32_bf16 v[106:109], v[170:173], v[220:223], v[106:109]
	v_mfma_f32_16x16x32_bf16 v[94:97], v[162:165], v[228:231], v[94:97]
	v_mfma_f32_16x16x32_bf16 v[90:93], v[170:173], v[228:231], v[90:93]
	v_mfma_f32_16x16x32_bf16 v[78:81], v[162:165], v[236:239], v[78:81]
	v_mfma_f32_16x16x32_bf16 v[74:77], v[170:173], v[236:239], v[74:77]
	s_setprio 0
	s_setprio 1
	v_mfma_f32_16x16x32_bf16 v[126:129], v[166:169], v[216:219], v[126:129]
	v_mfma_f32_16x16x32_bf16 v[122:125], v[174:177], v[216:219], v[122:125]
	v_mfma_f32_16x16x32_bf16 v[110:113], v[166:169], v[224:227], v[110:113]
	v_mfma_f32_16x16x32_bf16 v[106:109], v[174:177], v[224:227], v[106:109]
	v_mfma_f32_16x16x32_bf16 v[94:97], v[166:169], v[232:235], v[94:97]
	v_mfma_f32_16x16x32_bf16 v[90:93], v[174:177], v[232:235], v[90:93]
	v_mfma_f32_16x16x32_bf16 v[78:81], v[166:169], v[240:243], v[78:81]
	v_mfma_f32_16x16x32_bf16 v[74:77], v[174:177], v[240:243], v[74:77]
	s_setprio 0
	s_setprio 1
	v_mfma_f32_16x16x32_bf16 v[118:121], v[178:181], v[212:215], v[118:121]
	v_mfma_f32_16x16x32_bf16 v[114:117], v[204:207], v[212:215], v[114:117]
	v_mfma_f32_16x16x32_bf16 v[102:105], v[178:181], v[220:223], v[102:105]
	v_mfma_f32_16x16x32_bf16 v[98:101], v[204:207], v[220:223], v[98:101]
	v_mfma_f32_16x16x32_bf16 v[86:89], v[178:181], v[228:231], v[86:89]
	v_mfma_f32_16x16x32_bf16 v[82:85], v[204:207], v[228:231], v[82:85]
	v_mfma_f32_16x16x32_bf16 v[70:73], v[178:181], v[236:239], v[70:73]
	v_mfma_f32_16x16x32_bf16 v[66:69], v[204:207], v[236:239], v[66:69]
	s_setprio 0
	s_setprio 1
	v_mfma_f32_16x16x32_bf16 v[118:121], v[182:185], v[216:219], v[118:121]
	v_mfma_f32_16x16x32_bf16 v[114:117], v[208:211], v[216:219], v[114:117]
	v_mfma_f32_16x16x32_bf16 v[102:105], v[182:185], v[224:227], v[102:105]
	v_mfma_f32_16x16x32_bf16 v[98:101], v[208:211], v[224:227], v[98:101]
	v_mfma_f32_16x16x32_bf16 v[86:89], v[182:185], v[232:235], v[86:89]
	v_mfma_f32_16x16x32_bf16 v[82:85], v[208:211], v[232:235], v[82:85]
	v_mfma_f32_16x16x32_bf16 v[70:73], v[182:185], v[240:243], v[70:73]
	v_mfma_f32_16x16x32_bf16 v[66:69], v[208:211], v[240:243], v[66:69]
	s_setprio 0
	s_barrier
; #define PG8_STAGE(bufoff, gbase, voff) do { _Pragma("unroll") for (int _i = 0; _i < 2; ++_i) \
;         __builtin_amdgcn_global_load_lds((const unsigned*)((const char*)(gbase) + (voff)[_i]), (PG8_LAS unsigned*)(lds + (bufoff) + ldsw + _i * 8192), 16, 0, 0); } while (0)
; #define PG8_LDA(dst, b, h) do { _Pragma("unroll") for (int m = 0; m < 4; ++m) _Pragma("unroll") for (int k = 0; k < 2; ++k) dst[m][k] = *(const PG8_LAS bf16x8*)(lds + PG8_SA(b, h) + aoff + m * 2048 + k * 1024); } while (0)
; #define PG8_MMA(ai, bj, At, Bt) do { __builtin_amdgcn_s_setprio(1); _Pragma("unroll") for (int m = 0; m < 4; ++m) _Pragma("unroll") for (int n = 0; n < 2; ++n) _Pragma("unroll") for (int k = 0; k < 2; ++k) \
;         acc[ai][bj][m][n] = __builtin_amdgcn_mfma_f32_16x16x32_bf16(Bt[n][k], At[m][k], acc[ai][bj][m][n], 0, 0, 0); __builtin_amdgcn_s_setprio(0); } while (0)
; #define PG8_WAIT_V(n) asm volatile("s_waitcnt vmcnt(" #n ")" ::: "memory")
; #define PG8_WAIT_L(n) asm volatile("s_waitcnt lgkmcnt(" #n ")" ::: "memory")
; #define PG8_BAR __builtin_amdgcn_s_barrier()
; #define PG8_SCHED __builtin_amdgcn_sched_barrier(0)
; template <class Epi, class Sched, bool ALIGN_EPI = false, bool SP2 = false>
; __device__ __forceinline__ void gemm_phase(PG8_LAS unsigned char* lds, const Gemm g, const Sched& S, const Epi& E) {
;     ...
;             PG8_LDA(At, 1, 1); PG8_STAGE(PG8_SB(1, 0), b3, voffB); PG8_STAGE(PG8_SB(1, 1), b3 + hstep, voffB); PG8_STAGE(PG8_SA(1, 0), a3, voffA);
;             PG8_WAIT_V(8); PG8_WAIT_L(0); PG8_BAR; PG8_MMA(1, 0, At, B0); PG8_MMA(1, 1, At, B1); PG8_BAR; PG8_SCHED;
;     ...
;         if constexpr (ALIGN_EPI) { if (wr == 0) PG8_BAR; }
	s_add_i32 s47, s47, s54
	v_lshl_add_u64 v[158:159], v[158:159], 0, s[68:69]
	s_mov_b32 m0, s47
	ds_read_b128 v[212:215], v161 offset:49152
	ds_read_b128 v[216:219], v161 offset:50176
	ds_read_b128 v[220:223], v161 offset:51200
	ds_read_b128 v[224:227], v161 offset:52224
	ds_read_b128 v[228:231], v161 offset:53248
	ds_read_b128 v[232:235], v161 offset:54272
	ds_read_b128 v[236:239], v161 offset:55296
	ds_read_b128 v[240:243], v161 offset:56320
	global_load_lds_dwordx4 v[158:159], off
	s_add_i32 m0, s47, 0x2000
	s_add_u32 s18, s18, 0x80080
	v_lshl_add_u64 v[158:159], v[186:187], 0, s[68:69]
	s_addc_u32 s19, s19, 0
	s_add_i32 s47, s76, s54
	global_load_lds_dwordx4 v[158:159], off
	v_lshl_add_u64 v[158:159], s[18:19], 0, v[148:149]
	s_mov_b32 m0, s47
	s_nop 0
	global_load_lds_dwordx4 v[158:159], off
	v_lshl_add_u64 v[158:159], s[18:19], 0, v[144:145]
	s_add_i32 m0, s47, 0x2000
	s_nop 0
	global_load_lds_dwordx4 v[158:159], off
	v_lshl_add_u64 v[158:159], v[244:245], 0, s[68:69]
	s_mov_b32 m0, s5
	s_nop 0
	global_load_lds_dwordx4 v[158:159], off
	v_lshl_add_u64 v[158:159], v[246:247], 0, s[68:69]
	s_mov_b32 m0, s57
	s_nop 0
	global_load_lds_dwordx4 v[158:159], off
	s_nop 0
	s_waitcnt vmcnt(8)
	s_waitcnt lgkmcnt(0)
	s_setprio 1
	s_barrier
	v_mfma_f32_16x16x32_bf16 v[62:65], v[162:165], v[212:215], v[62:65]
	v_mfma_f32_16x16x32_bf16 v[58:61], v[170:173], v[212:215], v[58:61]
	v_mfma_f32_16x16x32_bf16 v[46:49], v[162:165], v[220:223], v[46:49]
	v_mfma_f32_16x16x32_bf16 v[42:45], v[170:173], v[220:223], v[42:45]
	v_mfma_f32_16x16x32_bf16 v[30:33], v[162:165], v[228:231], v[30:33]
	v_mfma_f32_16x16x32_bf16 v[26:29], v[170:173], v[228:231], v[26:29]
	v_mfma_f32_16x16x32_bf16 v[14:17], v[162:165], v[236:239], v[14:17]
	v_mfma_f32_16x16x32_bf16 v[10:13], v[170:173], v[236:239], v[10:13]
	s_setprio 0
	s_setprio 1
	v_mfma_f32_16x16x32_bf16 v[62:65], v[166:169], v[216:219], v[62:65]
	v_mfma_f32_16x16x32_bf16 v[58:61], v[174:177], v[216:219], v[58:61]
	v_mfma_f32_16x16x32_bf16 v[46:49], v[166:169], v[224:227], v[46:49]
	v_mfma_f32_16x16x32_bf16 v[42:45], v[174:177], v[224:227], v[42:45]
	v_mfma_f32_16x16x32_bf16 v[30:33], v[166:169], v[232:235], v[30:33]
	v_mfma_f32_16x16x32_bf16 v[26:29], v[174:177], v[232:235], v[26:29]
	v_mfma_f32_16x16x32_bf16 v[14:17], v[166:169], v[240:243], v[14:17]
	v_mfma_f32_16x16x32_bf16 v[10:13], v[174:177], v[240:243], v[10:13]
	s_setprio 0
	s_setprio 1
	v_mfma_f32_16x16x32_bf16 v[54:57], v[178:181], v[212:215], v[54:57]
	v_mfma_f32_16x16x32_bf16 v[50:53], v[204:207], v[212:215], v[50:53]
	v_mfma_f32_16x16x32_bf16 v[38:41], v[178:181], v[220:223], v[38:41]
	v_mfma_f32_16x16x32_bf16 v[34:37], v[204:207], v[220:223], v[34:37]
	v_mfma_f32_16x16x32_bf16 v[22:25], v[178:181], v[228:231], v[22:25]
	v_mfma_f32_16x16x32_bf16 v[18:21], v[204:207], v[228:231], v[18:21]
	v_mfma_f32_16x16x32_bf16 v[6:9], v[178:181], v[236:239], v[6:9]
	v_mfma_f32_16x16x32_bf16 v[2:5], v[204:207], v[236:239], v[2:5]
	s_setprio 0
	s_setprio 1
	v_mfma_f32_16x16x32_bf16 v[54:57], v[182:185], v[216:219], v[54:57]
	v_mfma_f32_16x16x32_bf16 v[50:53], v[208:211], v[216:219], v[50:53]
	v_mfma_f32_16x16x32_bf16 v[38:41], v[182:185], v[224:227], v[38:41]
	v_mfma_f32_16x16x32_bf16 v[34:37], v[208:211], v[224:227], v[34:37]
	v_mfma_f32_16x16x32_bf16 v[22:25], v[182:185], v[232:235], v[22:25]
	v_mfma_f32_16x16x32_bf16 v[18:21], v[208:211], v[232:235], v[18:21]
	v_mfma_f32_16x16x32_bf16 v[6:9], v[182:185], v[240:243], v[6:9]
	v_mfma_f32_16x16x32_bf16 v[2:5], v[208:211], v[240:243], v[2:5]
	s_setprio 0
	s_barrier
	s_add_i32 s46, s46, 2
	s_add_u32 s0, s0, 0x100
	s_addc_u32 s1, s1, 0
	s_add_u32 s78, s78, 0x100
	s_addc_u32 s79, s79, 0
	s_cmp_gt_u32 s46, 29
	s_cbranch_scc0 .LBB0_76
	s_and_b64 vcc, exec, s[42:43]
	s_cbranch_vccz .LBB0_79
	s_barrier

; #define PG8_STAGE(bufoff, gbase, voff) do { _Pragma("unroll") for (int _i = 0; _i < 2; ++_i) \
;         __builtin_amdgcn_global_load_lds((const unsigned*)((const char*)(gbase) + (voff)[_i]), (PG8_LAS unsigned*)(lds + (bufoff) + ldsw + _i * 8192), 16, 0, 0); } while (0)
; #define PG8_LDA(dst, b, h) do { _Pragma("unroll") for (int m = 0; m < 4; ++m) _Pragma("unroll") for (int k = 0; k < 2; ++k) dst[m][k] = *(const PG8_LAS bf16x8*)(lds + PG8_SA(b, h) + aoff + m * 2048 + k * 1024); } while (0)
; #define PG8_LDB(dst, b, h) do { _Pragma("unroll") for (int n = 0; n < 2; ++n) _Pragma("unroll") for (int k = 0; k < 2; ++k) dst[n][k] = *(const PG8_LAS bf16x8*)(lds + PG8_SB(b, h) + boff + n * 2048 + k * 1024); } while (0)
; #define PG8_WAIT_V(n) asm volatile("s_waitcnt vmcnt(" #n ")" ::: "memory")
; #define PG8_WAIT_L(n) asm volatile("s_waitcnt lgkmcnt(" #n ")" ::: "memory")
; #define PG8_BAR __builtin_amdgcn_s_barrier()
; #define PG8_SCHED __builtin_amdgcn_sched_barrier(0)
; template <class Epi, class Sched, bool ALIGN_EPI = false, bool SP2 = false>
; __device__ __forceinline__ void gemm_phase(PG8_LAS unsigned char* lds, const Gemm g, const Sched& S, const Epi& E) {
;     ...
;         const char* nA = has_next ? (const char*)g.A + (size_t)nxt.pm * tstep : cA; const char* nB = has_next ? (const char*)g.Bt + (size_t)nxt.pn * tstep : cB;
;         for (int t = 0; t < nt; t += 2) {
;             const bool last = (t == nt - 2);
;             const char* a1 = cA + (size_t)(t + 1) * kstep;
;             const char* a2 = last ? nA : cA + (size_t)(t + 2) * kstep; const char* b2 = last ? nB : cB + (size_t)(t + 2) * kstep;
;             const char* a3 = a2 + kstep; const char* b3 = b2 + kstep;
;             if (last && has_next) S.a_ready(nxt);
;             if constexpr (SP2) {
;             PG8_LDB(B0, 0, 0); PG8_LDB(B1, 0, 1); PG8_SCHED; PG8_LDA(At, 0, 0); PG8_STAGE(PG8_SA(1, 1), a1 + hstep, voffA);
;             PG8_WAIT_V(8); PG8_WAIT_L(0); PG8_BAR; PG8_MMA(0, 0, At, B0); PG8_MMA(0, 1, At, B1); PG8_BAR; PG8_SCHED;
;             PG8_LDA(At, 0, 1); PG8_STAGE(PG8_SB(0, 0), b2, voffB); PG8_STAGE(PG8_SB(0, 1), b2 + hstep, voffB); PG8_STAGE(PG8_SA(0, 0), a2, voffA);
;             PG8_WAIT_V(8); PG8_WAIT_L(0); PG8_BAR; PG8_MMA(1, 0, At, B0); PG8_MMA(1, 1, At, B1); PG8_BAR; PG8_SCHED;
.LBB0_98:
	s_add_u32 s40, vcc_lo, 0xfff80080
	s_addc_u32 s41, vcc_hi, -1
	s_add_i32 s47, 0, 0x10000
	s_cmp_eq_u32 s46, 28
	s_cselect_b32 s59, s97, s41
	s_cselect_b32 s58, s84, s40
	s_cselect_b32 s41, s85, s79
	s_cselect_b32 s40, s95, s78
	s_add_i32 s80, 0, 0x14000
	v_add_u32_e32 v170, s47, v143
	v_add_u32_e32 v186, s80, v143
	ds_read_b128 v[156:159], v170
	ds_read_b128 v[162:165], v170 offset:1024
	ds_read_b128 v[166:169], v170 offset:2048
	ds_read_b128 v[170:173], v170 offset:3072
	ds_read_b128 v[174:177], v186
	ds_read_b128 v[178:181], v186 offset:1024
	ds_read_b128 v[182:185], v186 offset:2048
	ds_read_b128 v[204:207], v186 offset:3072
	v_lshl_add_u64 v[186:187], vcc, 0, v[152:153]
	s_add_i32 m0, s5, 0xc000
	ds_read_b128 v[208:211], v161
	ds_read_b128 v[212:215], v161 offset:1024
	ds_read_b128 v[216:219], v161 offset:2048
	ds_read_b128 v[220:223], v161 offset:3072
	ds_read_b128 v[224:227], v161 offset:4096
	ds_read_b128 v[228:231], v161 offset:5120
	ds_read_b128 v[232:235], v161 offset:6144
	ds_read_b128 v[236:239], v161 offset:7168
	global_load_lds_dwordx4 v[186:187], off
	v_lshl_add_u64 v[186:187], vcc, 0, v[154:155]
	s_add_i32 m0, s5, 0xe000
	s_nop 0
	global_load_lds_dwordx4 v[186:187], off
	s_waitcnt vmcnt(8)
	s_waitcnt lgkmcnt(0)
	s_setprio 1
	s_barrier
	v_mfma_f32_16x16x32_bf16 v[126:129], v[156:159], v[208:211], v[126:129]
	v_mfma_f32_16x16x32_bf16 v[122:125], v[166:169], v[208:211], v[122:125]
	v_mfma_f32_16x16x32_bf16 v[110:113], v[156:159], v[216:219], v[110:113]
	v_mfma_f32_16x16x32_bf16 v[106:109], v[166:169], v[216:219], v[106:109]
	v_mfma_f32_16x16x32_bf16 v[94:97], v[156:159], v[224:227], v[94:97]
	v_mfma_f32_16x16x32_bf16 v[90:93], v[166:169], v[224:227], v[90:93]
	v_mfma_f32_16x16x32_bf16 v[78:81], v[156:159], v[232:235], v[78:81]
	v_mfma_f32_16x16x32_bf16 v[74:77], v[166:169], v[232:235], v[74:77]
	s_setprio 0
	s_setprio 1
	v_mfma_f32_16x16x32_bf16 v[126:129], v[162:165], v[212:215], v[126:129]
	v_mfma_f32_16x16x32_bf16 v[122:125], v[170:173], v[212:215], v[122:125]
	v_mfma_f32_16x16x32_bf16 v[110:113], v[162:165], v[220:223], v[110:113]
	v_mfma_f32_16x16x32_bf16 v[106:109], v[170:173], v[220:223], v[106:109]
	v_mfma_f32_16x16x32_bf16 v[94:97], v[162:165], v[228:231], v[94:97]
	v_mfma_f32_16x16x32_bf16 v[90:93], v[170:173], v[228:231], v[90:93]
	v_mfma_f32_16x16x32_bf16 v[78:81], v[162:165], v[236:239], v[78:81]
	v_mfma_f32_16x16x32_bf16 v[74:77], v[170:173], v[236:239], v[74:77]
	s_setprio 0
	s_setprio 1
	v_mfma_f32_16x16x32_bf16 v[118:121], v[174:177], v[208:211], v[118:121]
	v_mfma_f32_16x16x32_bf16 v[114:117], v[182:185], v[208:211], v[114:117]
	v_mfma_f32_16x16x32_bf16 v[102:105], v[174:177], v[216:219], v[102:105]
	v_mfma_f32_16x16x32_bf16 v[98:101], v[182:185], v[216:219], v[98:101]
	v_mfma_f32_16x16x32_bf16 v[86:89], v[174:177], v[224:227], v[86:89]
	v_mfma_f32_16x16x32_bf16 v[82:85], v[182:185], v[224:227], v[82:85]
	v_mfma_f32_16x16x32_bf16 v[70:73], v[174:177], v[232:235], v[70:73]
	v_mfma_f32_16x16x32_bf16 v[66:69], v[182:185], v[232:235], v[66:69]
	s_setprio 0
	s_setprio 1
	v_mfma_f32_16x16x32_bf16 v[118:121], v[178:181], v[212:215], v[118:121]
	v_mfma_f32_16x16x32_bf16 v[114:117], v[204:207], v[212:215], v[114:117]
	v_mfma_f32_16x16x32_bf16 v[102:105], v[178:181], v[220:223], v[102:105]
	v_mfma_f32_16x16x32_bf16 v[98:101], v[204:207], v[220:223], v[98:101]
	v_mfma_f32_16x16x32_bf16 v[86:89], v[178:181], v[228:231], v[86:89]
	v_mfma_f32_16x16x32_bf16 v[82:85], v[204:207], v[228:231], v[82:85]
	v_mfma_f32_16x16x32_bf16 v[70:73], v[178:181], v[236:239], v[70:73]
	v_mfma_f32_16x16x32_bf16 v[66:69], v[204:207], v[236:239], v[66:69]
	s_setprio 0
	s_barrier
	s_add_i32 s47, s47, s4
	v_lshl_add_u64 v[186:187], s[40:41], 0, v[148:149]
	s_mov_b32 m0, s47
	ds_read_b128 v[208:211], v161 offset:16384
	ds_read_b128 v[212:215], v161 offset:17408
	ds_read_b128 v[216:219], v161 offset:18432
	ds_read_b128 v[220:223], v161 offset:19456
	ds_read_b128 v[224:227], v161 offset:20480
	ds_read_b128 v[228:231], v161 offset:21504
	ds_read_b128 v[232:235], v161 offset:22528
	ds_read_b128 v[236:239], v161 offset:23552
	global_load_lds_dwordx4 v[186:187], off
	s_add_i32 m0, s47, 0x2000
	s_add_u32 s76, s40, 0x80000
	v_lshl_add_u64 v[240:241], s[40:41], 0, v[144:145]
	s_addc_u32 s77, s41, 0
	s_add_i32 s47, s80, s4
	global_load_lds_dwordx4 v[240:241], off
	v_lshl_add_u64 v[242:243], s[76:77], 0, v[148:149]
	s_mov_b32 m0, s47
	v_lshl_add_u64 v[244:245], s[58:59], 0, v[146:147]
	global_load_lds_dwordx4 v[242:243], off
	v_lshl_add_u64 v[242:243], s[76:77], 0, v[144:145]
	s_add_i32 m0, s47, 0x2000
	s_nop 0
	global_load_lds_dwordx4 v[242:243], off
	v_lshl_add_u64 v[242:243], s[58:59], 0, v[150:151]
	s_mov_b32 m0, s5
	s_nop 0
	global_load_lds_dwordx4 v[242:243], off
	s_mov_b32 m0, s30
	s_nop 0
	global_load_lds_dwordx4 v[244:245], off
	s_waitcnt vmcnt(8)
	s_waitcnt lgkmcnt(0)
	s_setprio 1
	s_barrier
; #define PG8_STAGE(bufoff, gbase, voff) do { _Pragma("unroll") for (int _i = 0; _i < 2; ++_i) \
;         __builtin_amdgcn_global_load_lds((const unsigned*)((const char*)(gbase) + (voff)[_i]), (PG8_LAS unsigned*)(lds + (bufoff) + ldsw + _i * 8192), 16, 0, 0); } while (0)
; #define PG8_LDA(dst, b, h) do { _Pragma("unroll") for (int m = 0; m < 4; ++m) _Pragma("unroll") for (int k = 0; k < 2; ++k) dst[m][k] = *(const PG8_LAS bf16x8*)(lds + PG8_SA(b, h) + aoff + m * 2048 + k * 1024); } while (0)
; #define PG8_LDB(dst, b, h) do { _Pragma("unroll") for (int n = 0; n < 2; ++n) _Pragma("unroll") for (int k = 0; k < 2; ++k) dst[n][k] = *(const PG8_LAS bf16x8*)(lds + PG8_SB(b, h) + boff + n * 2048 + k * 1024); } while (0)
; #define PG8_MMA(ai, bj, At, Bt) do { __builtin_amdgcn_s_setprio(1); _Pragma("unroll") for (int m = 0; m < 4; ++m) _Pragma("unroll") for (int n = 0; n < 2; ++n) _Pragma("unroll") for (int k = 0; k < 2; ++k) \
;         acc[ai][bj][m][n] = __builtin_amdgcn_mfma_f32_16x16x32_bf16(Bt[n][k], At[m][k], acc[ai][bj][m][n], 0, 0, 0); __builtin_amdgcn_s_setprio(0); } while (0)
; #define PG8_WAIT_V(n) asm volatile("s_waitcnt vmcnt(" #n ")" ::: "memory")
; #define PG8_WAIT_L(n) asm volatile("s_waitcnt lgkmcnt(" #n ")" ::: "memory")
; #define PG8_BAR __builtin_amdgcn_s_barrier()
; #define PG8_SCHED __builtin_amdgcn_sched_barrier(0)
; template <class Epi, class Sched, bool ALIGN_EPI = false, bool SP2 = false>
; __device__ __forceinline__ void gemm_phase(PG8_LAS unsigned char* lds, const Gemm g, const Sched& S, const Epi& E) {
;     ...
;             PG8_WAIT_V(8); PG8_WAIT_L(0); PG8_BAR; PG8_MMA(1, 0, At, B0); PG8_MMA(1, 1, At, B1); PG8_BAR; PG8_SCHED;
;             PG8_LDB(B0, 1, 0); PG8_LDB(B1, 1, 1); PG8_SCHED; PG8_LDA(At, 1, 0); PG8_STAGE(PG8_SA(0, 1), a2 + hstep, voffA);
;             PG8_WAIT_V(8); PG8_WAIT_L(0); PG8_BAR; PG8_MMA(0, 0, At, B0); PG8_MMA(0, 1, At, B1); PG8_BAR; PG8_SCHED;
	v_mfma_f32_16x16x32_bf16 v[62:65], v[156:159], v[208:211], v[62:65]
	v_mfma_f32_16x16x32_bf16 v[58:61], v[166:169], v[208:211], v[58:61]
	v_mfma_f32_16x16x32_bf16 v[46:49], v[156:159], v[216:219], v[46:49]
	v_mfma_f32_16x16x32_bf16 v[42:45], v[166:169], v[216:219], v[42:45]
	v_mfma_f32_16x16x32_bf16 v[30:33], v[156:159], v[224:227], v[30:33]
	v_mfma_f32_16x16x32_bf16 v[26:29], v[166:169], v[224:227], v[26:29]
	v_mfma_f32_16x16x32_bf16 v[14:17], v[156:159], v[232:235], v[14:17]
	v_mfma_f32_16x16x32_bf16 v[10:13], v[166:169], v[232:235], v[10:13]
	s_setprio 0
	s_setprio 1
	v_mfma_f32_16x16x32_bf16 v[62:65], v[162:165], v[212:215], v[62:65]
	v_mfma_f32_16x16x32_bf16 v[58:61], v[170:173], v[212:215], v[58:61]
	v_mfma_f32_16x16x32_bf16 v[46:49], v[162:165], v[220:223], v[46:49]
	v_mfma_f32_16x16x32_bf16 v[42:45], v[170:173], v[220:223], v[42:45]
	v_mfma_f32_16x16x32_bf16 v[30:33], v[162:165], v[228:231], v[30:33]
	v_mfma_f32_16x16x32_bf16 v[26:29], v[170:173], v[228:231], v[26:29]
	v_mfma_f32_16x16x32_bf16 v[14:17], v[162:165], v[236:239], v[14:17]
	v_mfma_f32_16x16x32_bf16 v[10:13], v[170:173], v[236:239], v[10:13]
	s_setprio 0
	s_setprio 1
	v_mfma_f32_16x16x32_bf16 v[54:57], v[174:177], v[208:211], v[54:57]
	v_mfma_f32_16x16x32_bf16 v[50:53], v[182:185], v[208:211], v[50:53]
	v_mfma_f32_16x16x32_bf16 v[38:41], v[174:177], v[216:219], v[38:41]
	v_mfma_f32_16x16x32_bf16 v[34:37], v[182:185], v[216:219], v[34:37]
	v_mfma_f32_16x16x32_bf16 v[22:25], v[174:177], v[224:227], v[22:25]
	v_mfma_f32_16x16x32_bf16 v[18:21], v[182:185], v[224:227], v[18:21]
	v_mfma_f32_16x16x32_bf16 v[6:9], v[174:177], v[232:235], v[6:9]
	v_mfma_f32_16x16x32_bf16 v[2:5], v[182:185], v[232:235], v[2:5]
	s_setprio 0
	s_setprio 1
	v_mfma_f32_16x16x32_bf16 v[54:57], v[178:181], v[212:215], v[54:57]
	v_mfma_f32_16x16x32_bf16 v[50:53], v[204:207], v[212:215], v[50:53]
	v_mfma_f32_16x16x32_bf16 v[38:41], v[178:181], v[220:223], v[38:41]
	v_mfma_f32_16x16x32_bf16 v[34:37], v[204:207], v[220:223], v[34:37]
	v_mfma_f32_16x16x32_bf16 v[22:25], v[178:181], v[228:231], v[22:25]
	v_mfma_f32_16x16x32_bf16 v[18:21], v[204:207], v[228:231], v[18:21]
	v_mfma_f32_16x16x32_bf16 v[6:9], v[178:181], v[236:239], v[6:9]
	v_mfma_f32_16x16x32_bf16 v[2:5], v[204:207], v[236:239], v[2:5]
	s_setprio 0
	s_barrier
	s_add_i32 s47, 0, 0x18000
	s_add_i32 s76, 0, 0x1c000
	v_add_u32_e32 v170, s47, v143
	v_add_u32_e32 v203, s76, v143
	ds_read_b128 v[156:159], v170
	ds_read_b128 v[162:165], v170 offset:1024
	ds_read_b128 v[166:169], v170 offset:2048
	ds_read_b128 v[170:173], v170 offset:3072
	ds_read_b128 v[174:177], v203
	ds_read_b128 v[178:181], v203 offset:1024
	ds_read_b128 v[182:185], v203 offset:2048
	ds_read_b128 v[204:207], v203 offset:3072
	s_add_u32 s58, s58, 0x80000
	s_addc_u32 s59, s59, 0
	s_mov_b32 m0, s34
	v_lshl_add_u64 v[246:247], s[58:59], 0, v[150:151]
	ds_read_b128 v[208:211], v161 offset:32768
	ds_read_b128 v[212:215], v161 offset:33792
	ds_read_b128 v[216:219], v161 offset:34816
	ds_read_b128 v[220:223], v161 offset:35840
	ds_read_b128 v[224:227], v161 offset:36864
	ds_read_b128 v[228:231], v161 offset:37888
	ds_read_b128 v[232:235], v161 offset:38912
	ds_read_b128 v[236:239], v161 offset:39936
	global_load_lds_dwordx4 v[246:247], off
	v_lshl_add_u64 v[246:247], s[58:59], 0, v[146:147]
	s_mov_b32 m0, s57
	s_nop 0
	global_load_lds_dwordx4 v[246:247], off
	s_waitcnt vmcnt(8)
	s_waitcnt lgkmcnt(0)
	s_setprio 1
	s_barrier
	v_mfma_f32_16x16x32_bf16 v[126:129], v[156:159], v[208:211], v[126:129]
	v_mfma_f32_16x16x32_bf16 v[122:125], v[166:169], v[208:211], v[122:125]
	v_mfma_f32_16x16x32_bf16 v[110:113], v[156:159], v[216:219], v[110:113]
	v_mfma_f32_16x16x32_bf16 v[106:109], v[166:169], v[216:219], v[106:109]
	v_mfma_f32_16x16x32_bf16 v[94:97], v[156:159], v[224:227], v[94:97]
	v_mfma_f32_16x16x32_bf16 v[90:93], v[166:169], v[224:227], v[90:93]
	v_mfma_f32_16x16x32_bf16 v[78:81], v[156:159], v[232:235], v[78:81]
	v_mfma_f32_16x16x32_bf16 v[74:77], v[166:169], v[232:235], v[74:77]
	s_setprio 0
	s_setprio 1
	v_mfma_f32_16x16x32_bf16 v[126:129], v[162:165], v[212:215], v[126:129]
	v_mfma_f32_16x16x32_bf16 v[122:125], v[170:173], v[212:215], v[122:125]
	v_mfma_f32_16x16x32_bf16 v[110:113], v[162:165], v[220:223], v[110:113]
	v_mfma_f32_16x16x32_bf16 v[106:109], v[170:173], v[220:223], v[106:109]
	v_mfma_f32_16x16x32_bf16 v[94:97], v[162:165], v[228:231], v[94:97]
	v_mfma_f32_16x16x32_bf16 v[90:93], v[170:173], v[228:231], v[90:93]
	v_mfma_f32_16x16x32_bf16 v[78:81], v[162:165], v[236:239], v[78:81]
	v_mfma_f32_16x16x32_bf16 v[74:77], v[170:173], v[236:239], v[74:77]
	s_setprio 0
	s_setprio 1
	v_mfma_f32_16x16x32_bf16 v[118:121], v[174:177], v[208:211], v[118:121]
	v_mfma_f32_16x16x32_bf16 v[114:117], v[182:185], v[208:211], v[114:117]
	v_mfma_f32_16x16x32_bf16 v[102:105], v[174:177], v[216:219], v[102:105]
	v_mfma_f32_16x16x32_bf16 v[98:101], v[182:185], v[216:219], v[98:101]
	v_mfma_f32_16x16x32_bf16 v[86:89], v[174:177], v[224:227], v[86:89]
	v_mfma_f32_16x16x32_bf16 v[82:85], v[182:185], v[224:227], v[82:85]
	v_mfma_f32_16x16x32_bf16 v[70:73], v[174:177], v[232:235], v[70:73]
	v_mfma_f32_16x16x32_bf16 v[66:69], v[182:185], v[232:235], v[66:69]
	s_setprio 0
	s_setprio 1
	v_mfma_f32_16x16x32_bf16 v[118:121], v[178:181], v[212:215], v[118:121]
	v_mfma_f32_16x16x32_bf16 v[114:117], v[204:207], v[212:215], v[114:117]
	v_mfma_f32_16x16x32_bf16 v[102:105], v[178:181], v[220:223], v[102:105]
	v_mfma_f32_16x16x32_bf16 v[98:101], v[204:207], v[220:223], v[98:101]
	v_mfma_f32_16x16x32_bf16 v[86:89], v[178:181], v[228:231], v[86:89]
	v_mfma_f32_16x16x32_bf16 v[82:85], v[204:207], v[228:231], v[82:85]
	v_mfma_f32_16x16x32_bf16 v[70:73], v[178:181], v[236:239], v[70:73]
	v_mfma_f32_16x16x32_bf16 v[66:69], v[204:207], v[236:239], v[66:69]
	s_setprio 0
	s_barrier
; #define PG8_STAGE(bufoff, gbase, voff) do { _Pragma("unroll") for (int _i = 0; _i < 2; ++_i) \
;         __builtin_amdgcn_global_load_lds((const unsigned*)((const char*)(gbase) + (voff)[_i]), (PG8_LAS unsigned*)(lds + (bufoff) + ldsw + _i * 8192), 16, 0, 0); } while (0)
; #define PG8_LDA(dst, b, h) do { _Pragma("unroll") for (int m = 0; m < 4; ++m) _Pragma("unroll") for (int k = 0; k < 2; ++k) dst[m][k] = *(const PG8_LAS bf16x8*)(lds + PG8_SA(b, h) + aoff + m * 2048 + k * 1024); } while (0)
; #define PG8_MMA(ai, bj, At, Bt) do { __builtin_amdgcn_s_setprio(1); _Pragma("unroll") for (int m = 0; m < 4; ++m) _Pragma("unroll") for (int n = 0; n < 2; ++n) _Pragma("unroll") for (int k = 0; k < 2; ++k) \
;         acc[ai][bj][m][n] = __builtin_amdgcn_mfma_f32_16x16x32_bf16(Bt[n][k], At[m][k], acc[ai][bj][m][n], 0, 0, 0); __builtin_amdgcn_s_setprio(0); } while (0)
; #define PG8_WAIT_V(n) asm volatile("s_waitcnt vmcnt(" #n ")" ::: "memory")
; #define PG8_WAIT_L(n) asm volatile("s_waitcnt lgkmcnt(" #n ")" ::: "memory")
; #define PG8_BAR __builtin_amdgcn_s_barrier()
; #define PG8_SCHED __builtin_amdgcn_sched_barrier(0)
;     __device__ __forceinline__ void operator()(const f32x4 (&acc)[2][2][4][2], const Unit& u, int wr, int wc, int fr, int fq) const {
;     ...
;             for (int m = 0; m < 4; ++m) { const size_t row = (size_t)(row0 + ai * HALF + m * 16); float ss = 0.f;
; #pragma unroll
;                 for (int bj = 0; bj < 2; ++bj) { const size_t off = row * DM + col0 + bj * HALF;
;                     f32x4 v0 = acc[ai][bj][m][0] + *(const f32x4*)(base + off), v1 = acc[ai][bj][m][1] + *(const f32x4*)(base + off + 4);
; template <class Epi, class Sched, bool ALIGN_EPI = false, bool SP2 = false>
; __device__ __forceinline__ void gemm_phase(PG8_LAS unsigned char* lds, const Gemm g, const Sched& S, const Epi& E) {
;     ...
;             PG8_LDA(At, 1, 1); PG8_STAGE(PG8_SB(1, 0), b3, voffB); PG8_STAGE(PG8_SB(1, 1), b3 + hstep, voffB); PG8_STAGE(PG8_SA(1, 0), a3, voffA);
;             PG8_WAIT_V(8); PG8_WAIT_L(0); PG8_BAR; PG8_MMA(1, 0, At, B0); PG8_MMA(1, 1, At, B1); PG8_BAR; PG8_SCHED;
	s_add_i32 s47, s47, s4
	v_lshl_add_u64 v[186:187], v[186:187], 0, s[68:69]
	s_mov_b32 m0, s47
	ds_read_b128 v[208:211], v161 offset:49152
	ds_read_b128 v[212:215], v161 offset:50176
	ds_read_b128 v[216:219], v161 offset:51200
	ds_read_b128 v[220:223], v161 offset:52224
	ds_read_b128 v[224:227], v161 offset:53248
	ds_read_b128 v[228:231], v161 offset:54272
	ds_read_b128 v[232:235], v161 offset:55296
	ds_read_b128 v[236:239], v161 offset:56320
	global_load_lds_dwordx4 v[186:187], off
	s_add_i32 m0, s47, 0x2000
	s_add_u32 s40, s40, 0x80080
	v_lshl_add_u64 v[186:187], v[240:241], 0, s[68:69]
	s_addc_u32 s41, s41, 0
	s_add_i32 s47, s76, s4
	global_load_lds_dwordx4 v[186:187], off
	v_lshl_add_u64 v[186:187], s[40:41], 0, v[148:149]
	s_mov_b32 m0, s47
	s_nop 0
	global_load_lds_dwordx4 v[186:187], off
	v_lshl_add_u64 v[186:187], s[40:41], 0, v[144:145]
	s_add_i32 m0, s47, 0x2000
	s_nop 0
	global_load_lds_dwordx4 v[186:187], off
	v_lshl_add_u64 v[186:187], v[242:243], 0, s[68:69]
	s_mov_b32 m0, s67
	s_nop 0
	global_load_lds_dwordx4 v[186:187], off
	v_lshl_add_u64 v[186:187], v[244:245], 0, s[68:69]
	s_mov_b32 m0, s28
	s_nop 0
	global_load_lds_dwordx4 v[186:187], off
	s_nop 0
	s_waitcnt vmcnt(8)
	s_waitcnt lgkmcnt(0)
	s_setprio 1
	s_barrier
	v_mfma_f32_16x16x32_bf16 v[62:65], v[156:159], v[208:211], v[62:65]
	v_mfma_f32_16x16x32_bf16 v[58:61], v[166:169], v[208:211], v[58:61]
	v_mfma_f32_16x16x32_bf16 v[46:49], v[156:159], v[216:219], v[46:49]
	v_mfma_f32_16x16x32_bf16 v[42:45], v[166:169], v[216:219], v[42:45]
	v_mfma_f32_16x16x32_bf16 v[30:33], v[156:159], v[224:227], v[30:33]
	v_mfma_f32_16x16x32_bf16 v[26:29], v[166:169], v[224:227], v[26:29]
	v_mfma_f32_16x16x32_bf16 v[14:17], v[156:159], v[232:235], v[14:17]
	v_mfma_f32_16x16x32_bf16 v[10:13], v[166:169], v[232:235], v[10:13]
	s_setprio 0
	s_setprio 1
	v_mfma_f32_16x16x32_bf16 v[62:65], v[162:165], v[212:215], v[62:65]
	v_mfma_f32_16x16x32_bf16 v[58:61], v[170:173], v[212:215], v[58:61]
	v_mfma_f32_16x16x32_bf16 v[46:49], v[162:165], v[220:223], v[46:49]
	v_mfma_f32_16x16x32_bf16 v[42:45], v[170:173], v[220:223], v[42:45]
	v_mfma_f32_16x16x32_bf16 v[30:33], v[162:165], v[228:231], v[30:33]
	v_mfma_f32_16x16x32_bf16 v[26:29], v[170:173], v[228:231], v[26:29]
	v_mfma_f32_16x16x32_bf16 v[14:17], v[162:165], v[236:239], v[14:17]
	v_mfma_f32_16x16x32_bf16 v[10:13], v[170:173], v[236:239], v[10:13]
	s_setprio 0
	s_setprio 1
	v_mfma_f32_16x16x32_bf16 v[54:57], v[174:177], v[208:211], v[54:57]
	v_mfma_f32_16x16x32_bf16 v[50:53], v[182:185], v[208:211], v[50:53]
	v_mfma_f32_16x16x32_bf16 v[38:41], v[174:177], v[216:219], v[38:41]
	v_mfma_f32_16x16x32_bf16 v[34:37], v[182:185], v[216:219], v[34:37]
	v_mfma_f32_16x16x32_bf16 v[22:25], v[174:177], v[224:227], v[22:25]
	v_mfma_f32_16x16x32_bf16 v[18:21], v[182:185], v[224:227], v[18:21]
	v_mfma_f32_16x16x32_bf16 v[6:9], v[174:177], v[232:235], v[6:9]
	v_mfma_f32_16x16x32_bf16 v[2:5], v[182:185], v[232:235], v[2:5]
	s_setprio 0
	s_setprio 1
	v_mfma_f32_16x16x32_bf16 v[54:57], v[178:181], v[212:215], v[54:57]
	v_mfma_f32_16x16x32_bf16 v[50:53], v[204:207], v[212:215], v[50:53]
	v_mfma_f32_16x16x32_bf16 v[38:41], v[178:181], v[220:223], v[38:41]
	v_mfma_f32_16x16x32_bf16 v[34:37], v[204:207], v[220:223], v[34:37]
	v_mfma_f32_16x16x32_bf16 v[22:25], v[178:181], v[228:231], v[22:25]
	v_mfma_f32_16x16x32_bf16 v[18:21], v[204:207], v[228:231], v[18:21]
	v_mfma_f32_16x16x32_bf16 v[6:9], v[178:181], v[236:239], v[6:9]
	v_mfma_f32_16x16x32_bf16 v[2:5], v[204:207], v[236:239], v[2:5]
	s_setprio 0
	s_barrier
	s_add_i32 s46, s46, 2
	s_add_u32 vcc_lo, vcc_lo, 0x100
	s_addc_u32 vcc_hi, vcc_hi, 0
	s_add_u32 s78, s78, 0x100
	s_addc_u32 s79, s79, 0
	s_cmp_gt_u32 s46, 29
	s_cbranch_scc0 .LBB0_98
	v_lshl_add_u32 v156, s73, 8, v1
	v_lshl_or_b32 v157, s54, 8, v160
	v_lshl_add_u32 v157, v156, 11, v157
	v_mov_b32_e32 v247, 0
	v_lshlrev_b32_e32 v246, 2, v157
	v_lshl_add_u64 v[162:163], s[8:9], 0, v[246:247]
	v_lshlrev_b32_e32 v246, 1, v157
	v_lshl_add_u64 v[244:245], s[70:71], 0, v[246:247]
	s_mov_b32 s41, 0
	global_load_dwordx4 v[164:167], v[162:163], off
	global_load_dwordx4 v[168:171], v[162:163], off offset:16
	global_load_dwordx4 v[172:175], v[162:163], off offset:512
	global_load_dwordx4 v[176:179], v[162:163], off offset:528
	s_mov_b32 s40, 0x20000
	v_lshl_add_u64 v[246:247], v[162:163], 0, s[40:41]
	global_load_dwordx4 v[180:183], v[246:247], off
	global_load_dwordx4 v[184:187], v[246:247], off offset:16
	global_load_dwordx4 v[204:207], v[246:247], off offset:512
	global_load_dwordx4 v[208:211], v[246:247], off offset:528
	s_mov_b32 s40, 0x40000
	v_lshl_add_u64 v[246:247], v[162:163], 0, s[40:41]
	global_load_dwordx4 v[212:215], v[246:247], off
	global_load_dwordx4 v[216:219], v[246:247], off offset:16
	global_load_dwordx4 v[220:223], v[246:247], off offset:512
	global_load_dwordx4 v[224:227], v[246:247], off offset:528
	s_mov_b32 s40, 0x60000
	v_lshl_add_u64 v[246:247], v[162:163], 0, s[40:41]
	global_load_dwordx4 v[228:231], v[246:247], off
	global_load_dwordx4 v[232:235], v[246:247], off offset:16
	global_load_dwordx4 v[236:239], v[246:247], off offset:512
	global_load_dwordx4 v[240:243], v[246:247], off offset:528
	s_and_b64 vcc, exec, s[36:37]
	s_cbranch_vccz .Lx1_nobar
	s_barrier

; #define PG8_STAGE(bufoff, gbase, voff) do { _Pragma("unroll") for (int _i = 0; _i < 2; ++_i) \
;         __builtin_amdgcn_global_load_lds((const unsigned*)((const char*)(gbase) + (voff)[_i]), (PG8_LAS unsigned*)(lds + (bufoff) + ldsw + _i * 8192), 16, 0, 0); } while (0)
; #define PG8_LDA(dst, b, h) do { _Pragma("unroll") for (int m = 0; m < 4; ++m) _Pragma("unroll") for (int k = 0; k < 2; ++k) dst[m][k] = *(const PG8_LAS bf16x8*)(lds + PG8_SA(b, h) + aoff + m * 2048 + k * 1024); } while (0)
; #define PG8_LDB(dst, b, h) do { _Pragma("unroll") for (int n = 0; n < 2; ++n) _Pragma("unroll") for (int k = 0; k < 2; ++k) dst[n][k] = *(const PG8_LAS bf16x8*)(lds + PG8_SB(b, h) + boff + n * 2048 + k * 1024); } while (0)
; #define PG8_WAIT_V(n) asm volatile("s_waitcnt vmcnt(" #n ")" ::: "memory")
; #define PG8_WAIT_L(n) asm volatile("s_waitcnt lgkmcnt(" #n ")" ::: "memory")
; #define PG8_BAR __builtin_amdgcn_s_barrier()
; #define PG8_SCHED __builtin_amdgcn_sched_barrier(0)
; template <class Epi, class Sched, bool ALIGN_EPI = false, bool SP2 = false>
; __device__ __forceinline__ void gemm_phase(PG8_LAS unsigned char* lds, const Gemm g, const Sched& S, const Epi& E) {
;     ...
;         const char* nA = has_next ? (const char*)g.A + (size_t)nxt.pm * tstep : cA; const char* nB = has_next ? (const char*)g.Bt + (size_t)nxt.pn * tstep : cB;
;         for (int t = 0; t < nt; t += 2) {
;             const bool last = (t == nt - 2);
;             const char* a1 = cA + (size_t)(t + 1) * kstep;
;             const char* a2 = last ? nA : cA + (size_t)(t + 2) * kstep; const char* b2 = last ? nB : cB + (size_t)(t + 2) * kstep;
;             const char* a3 = a2 + kstep; const char* b3 = b2 + kstep;
;             if (last && has_next) S.a_ready(nxt);
;             if constexpr (SP2) {
;             PG8_LDB(B0, 0, 0); PG8_LDB(B1, 0, 1); PG8_SCHED; PG8_LDA(At, 0, 0); PG8_STAGE(PG8_SA(1, 1), a1 + hstep, voffA);
;             PG8_WAIT_V(8); PG8_WAIT_L(0); PG8_BAR; PG8_MMA(0, 0, At, B0); PG8_MMA(0, 1, At, B1); PG8_BAR; PG8_SCHED;
;             PG8_LDA(At, 0, 1); PG8_STAGE(PG8_SB(0, 0), b2, voffB); PG8_STAGE(PG8_SB(0, 1), b2 + hstep, voffB); PG8_STAGE(PG8_SA(0, 0), a2, voffA);
;             PG8_WAIT_V(8); PG8_WAIT_L(0); PG8_BAR; PG8_MMA(1, 0, At, B0); PG8_MMA(1, 1, At, B1); PG8_BAR; PG8_SCHED;
.LBB0_136:
	s_add_u32 s18, s58, 0xfffe0080
	s_addc_u32 s19, s59, -1
	s_add_i32 s46, 0, 0x10000
	s_cmp_eq_u32 s79, 4
	s_cselect_b32 s63, s37, s19
	s_cselect_b32 s62, s73, s18
	s_cselect_b32 s19, s11, s78
	s_cselect_b32 s18, s84, s85
	s_add_i32 s76, 0, 0x14000
	v_add_u32_e32 v172, s46, v1
	v_add_u32_e32 v203, s76, v1
	ds_read_b128 v[160:163], v172
	ds_read_b128 v[164:167], v172 offset:1024
	ds_read_b128 v[168:171], v172 offset:2048
	ds_read_b128 v[172:175], v172 offset:3072
	ds_read_b128 v[176:179], v203
	ds_read_b128 v[180:183], v203 offset:1024
	ds_read_b128 v[184:187], v203 offset:2048
	ds_read_b128 v[204:207], v203 offset:3072
	v_lshl_add_u64 v[240:241], s[58:59], 0, v[156:157]
	s_add_i32 m0, s5, 0xc000
	ds_read_b128 v[208:211], v143
	ds_read_b128 v[212:215], v143 offset:1024
	ds_read_b128 v[216:219], v143 offset:2048
	ds_read_b128 v[220:223], v143 offset:3072
	ds_read_b128 v[224:227], v143 offset:4096
	ds_read_b128 v[228:231], v143 offset:5120
	ds_read_b128 v[232:235], v143 offset:6144
	ds_read_b128 v[236:239], v143 offset:7168
	global_load_lds_dwordx4 v[240:241], off
	v_lshl_add_u64 v[240:241], s[58:59], 0, v[158:159]
	s_add_i32 m0, s5, 0xe000
	s_nop 0
	global_load_lds_dwordx4 v[240:241], off
	s_nop 0
	s_waitcnt vmcnt(8)
	s_waitcnt lgkmcnt(0)
	s_setprio 1
	s_barrier
	v_mfma_f32_16x16x32_bf16 v[126:129], v[160:163], v[208:211], v[126:129]
	v_mfma_f32_16x16x32_bf16 v[122:125], v[168:171], v[208:211], v[122:125]
	v_mfma_f32_16x16x32_bf16 v[110:113], v[160:163], v[216:219], v[110:113]
	v_mfma_f32_16x16x32_bf16 v[106:109], v[168:171], v[216:219], v[106:109]
	v_mfma_f32_16x16x32_bf16 v[94:97], v[160:163], v[224:227], v[94:97]
	v_mfma_f32_16x16x32_bf16 v[90:93], v[168:171], v[224:227], v[90:93]
	v_mfma_f32_16x16x32_bf16 v[78:81], v[160:163], v[232:235], v[78:81]
	v_mfma_f32_16x16x32_bf16 v[74:77], v[168:171], v[232:235], v[74:77]
	s_setprio 0
	s_setprio 1
	v_mfma_f32_16x16x32_bf16 v[126:129], v[164:167], v[212:215], v[126:129]
	v_mfma_f32_16x16x32_bf16 v[122:125], v[172:175], v[212:215], v[122:125]
	v_mfma_f32_16x16x32_bf16 v[110:113], v[164:167], v[220:223], v[110:113]
	v_mfma_f32_16x16x32_bf16 v[106:109], v[172:175], v[220:223], v[106:109]
	v_mfma_f32_16x16x32_bf16 v[94:97], v[164:167], v[228:231], v[94:97]
	v_mfma_f32_16x16x32_bf16 v[90:93], v[172:175], v[228:231], v[90:93]
	v_mfma_f32_16x16x32_bf16 v[78:81], v[164:167], v[236:239], v[78:81]
	v_mfma_f32_16x16x32_bf16 v[74:77], v[172:175], v[236:239], v[74:77]
	s_setprio 0
	s_setprio 1
	v_mfma_f32_16x16x32_bf16 v[118:121], v[176:179], v[208:211], v[118:121]
	v_mfma_f32_16x16x32_bf16 v[114:117], v[184:187], v[208:211], v[114:117]
	v_mfma_f32_16x16x32_bf16 v[102:105], v[176:179], v[216:219], v[102:105]
	v_mfma_f32_16x16x32_bf16 v[98:101], v[184:187], v[216:219], v[98:101]
	v_mfma_f32_16x16x32_bf16 v[86:89], v[176:179], v[224:227], v[86:89]
	v_mfma_f32_16x16x32_bf16 v[82:85], v[184:187], v[224:227], v[82:85]
	v_mfma_f32_16x16x32_bf16 v[70:73], v[176:179], v[232:235], v[70:73]
	v_mfma_f32_16x16x32_bf16 v[66:69], v[184:187], v[232:235], v[66:69]
	s_setprio 0
	s_setprio 1
	v_mfma_f32_16x16x32_bf16 v[118:121], v[180:183], v[212:215], v[118:121]
	v_mfma_f32_16x16x32_bf16 v[114:117], v[204:207], v[212:215], v[114:117]
	v_mfma_f32_16x16x32_bf16 v[102:105], v[180:183], v[220:223], v[102:105]
	v_mfma_f32_16x16x32_bf16 v[98:101], v[204:207], v[220:223], v[98:101]
	v_mfma_f32_16x16x32_bf16 v[86:89], v[180:183], v[228:231], v[86:89]
	v_mfma_f32_16x16x32_bf16 v[82:85], v[204:207], v[228:231], v[82:85]
	v_mfma_f32_16x16x32_bf16 v[70:73], v[180:183], v[236:239], v[70:73]
	v_mfma_f32_16x16x32_bf16 v[66:69], v[204:207], v[236:239], v[66:69]
	s_setprio 0
	s_barrier
	s_add_i32 s46, s46, s4
	v_lshl_add_u64 v[240:241], s[18:19], 0, v[148:149]
	s_mov_b32 m0, s46
	ds_read_b128 v[208:211], v143 offset:16384
	ds_read_b128 v[212:215], v143 offset:17408
	ds_read_b128 v[216:219], v143 offset:18432
	ds_read_b128 v[220:223], v143 offset:19456
	ds_read_b128 v[224:227], v143 offset:20480
	ds_read_b128 v[228:231], v143 offset:21504
	ds_read_b128 v[232:235], v143 offset:22528
	ds_read_b128 v[236:239], v143 offset:23552
	global_load_lds_dwordx4 v[240:241], off
	s_add_i32 m0, s46, 0x2000
	s_add_u32 s46, s18, 0x20000
	v_lshl_add_u64 v[242:243], s[18:19], 0, v[144:145]
	s_addc_u32 s47, s19, 0
	s_add_i32 s76, s76, s4
	global_load_lds_dwordx4 v[242:243], off
	v_lshl_add_u64 v[244:245], s[46:47], 0, v[148:149]
	s_mov_b32 m0, s76
	v_lshl_add_u64 v[246:247], s[62:63], 0, v[146:147]
	global_load_lds_dwordx4 v[244:245], off
	v_lshl_add_u64 v[244:245], s[46:47], 0, v[144:145]
	s_add_i32 m0, s76, 0x2000
	s_nop 0
	global_load_lds_dwordx4 v[244:245], off
	v_lshl_add_u64 v[244:245], s[62:63], 0, v[150:151]
	s_mov_b32 m0, s5
	s_nop 0
	global_load_lds_dwordx4 v[244:245], off
	s_mov_b32 m0, s28
	s_nop 0
	global_load_lds_dwordx4 v[246:247], off
	s_waitcnt vmcnt(8)
	s_waitcnt lgkmcnt(0)
	s_setprio 1
	s_barrier
; #define PG8_STAGE(bufoff, gbase, voff) do { _Pragma("unroll") for (int _i = 0; _i < 2; ++_i) \
;         __builtin_amdgcn_global_load_lds((const unsigned*)((const char*)(gbase) + (voff)[_i]), (PG8_LAS unsigned*)(lds + (bufoff) + ldsw + _i * 8192), 16, 0, 0); } while (0)
; #define PG8_LDA(dst, b, h) do { _Pragma("unroll") for (int m = 0; m < 4; ++m) _Pragma("unroll") for (int k = 0; k < 2; ++k) dst[m][k] = *(const PG8_LAS bf16x8*)(lds + PG8_SA(b, h) + aoff + m * 2048 + k * 1024); } while (0)
; #define PG8_LDB(dst, b, h) do { _Pragma("unroll") for (int n = 0; n < 2; ++n) _Pragma("unroll") for (int k = 0; k < 2; ++k) dst[n][k] = *(const PG8_LAS bf16x8*)(lds + PG8_SB(b, h) + boff + n * 2048 + k * 1024); } while (0)
; #define PG8_MMA(ai, bj, At, Bt) do { __builtin_amdgcn_s_setprio(1); _Pragma("unroll") for (int m = 0; m < 4; ++m) _Pragma("unroll") for (int n = 0; n < 2; ++n) _Pragma("unroll") for (int k = 0; k < 2; ++k) \
;         acc[ai][bj][m][n] = __builtin_amdgcn_mfma_f32_16x16x32_bf16(Bt[n][k], At[m][k], acc[ai][bj][m][n], 0, 0, 0); __builtin_amdgcn_s_setprio(0); } while (0)
; #define PG8_WAIT_V(n) asm volatile("s_waitcnt vmcnt(" #n ")" ::: "memory")
; #define PG8_WAIT_L(n) asm volatile("s_waitcnt lgkmcnt(" #n ")" ::: "memory")
; #define PG8_BAR __builtin_amdgcn_s_barrier()
; #define PG8_SCHED __builtin_amdgcn_sched_barrier(0)
; template <class Epi, class Sched, bool ALIGN_EPI = false, bool SP2 = false>
; __device__ __forceinline__ void gemm_phase(PG8_LAS unsigned char* lds, const Gemm g, const Sched& S, const Epi& E) {
;     ...
;             PG8_WAIT_V(8); PG8_WAIT_L(0); PG8_BAR; PG8_MMA(1, 0, At, B0); PG8_MMA(1, 1, At, B1); PG8_BAR; PG8_SCHED;
;             PG8_LDB(B0, 1, 0); PG8_LDB(B1, 1, 1); PG8_SCHED; PG8_LDA(At, 1, 0); PG8_STAGE(PG8_SA(0, 1), a2 + hstep, voffA);
;             PG8_WAIT_V(8); PG8_WAIT_L(0); PG8_BAR; PG8_MMA(0, 0, At, B0); PG8_MMA(0, 1, At, B1); PG8_BAR; PG8_SCHED;
	v_mfma_f32_16x16x32_bf16 v[62:65], v[160:163], v[208:211], v[62:65]
	v_mfma_f32_16x16x32_bf16 v[58:61], v[168:171], v[208:211], v[58:61]
	v_mfma_f32_16x16x32_bf16 v[46:49], v[160:163], v[216:219], v[46:49]
	v_mfma_f32_16x16x32_bf16 v[42:45], v[168:171], v[216:219], v[42:45]
	v_mfma_f32_16x16x32_bf16 v[30:33], v[160:163], v[224:227], v[30:33]
	v_mfma_f32_16x16x32_bf16 v[26:29], v[168:171], v[224:227], v[26:29]
	v_mfma_f32_16x16x32_bf16 v[14:17], v[160:163], v[232:235], v[14:17]
	v_mfma_f32_16x16x32_bf16 v[10:13], v[168:171], v[232:235], v[10:13]
	s_setprio 0
	s_setprio 1
	v_mfma_f32_16x16x32_bf16 v[62:65], v[164:167], v[212:215], v[62:65]
	v_mfma_f32_16x16x32_bf16 v[58:61], v[172:175], v[212:215], v[58:61]
	v_mfma_f32_16x16x32_bf16 v[46:49], v[164:167], v[220:223], v[46:49]
	v_mfma_f32_16x16x32_bf16 v[42:45], v[172:175], v[220:223], v[42:45]
	v_mfma_f32_16x16x32_bf16 v[30:33], v[164:167], v[228:231], v[30:33]
	v_mfma_f32_16x16x32_bf16 v[26:29], v[172:175], v[228:231], v[26:29]
	v_mfma_f32_16x16x32_bf16 v[14:17], v[164:167], v[236:239], v[14:17]
	v_mfma_f32_16x16x32_bf16 v[10:13], v[172:175], v[236:239], v[10:13]
	s_setprio 0
	s_setprio 1
	v_mfma_f32_16x16x32_bf16 v[54:57], v[176:179], v[208:211], v[54:57]
	v_mfma_f32_16x16x32_bf16 v[50:53], v[184:187], v[208:211], v[50:53]
	v_mfma_f32_16x16x32_bf16 v[38:41], v[176:179], v[216:219], v[38:41]
	v_mfma_f32_16x16x32_bf16 v[34:37], v[184:187], v[216:219], v[34:37]
	v_mfma_f32_16x16x32_bf16 v[22:25], v[176:179], v[224:227], v[22:25]
	v_mfma_f32_16x16x32_bf16 v[18:21], v[184:187], v[224:227], v[18:21]
	v_mfma_f32_16x16x32_bf16 v[6:9], v[176:179], v[232:235], v[6:9]
	v_mfma_f32_16x16x32_bf16 v[2:5], v[184:187], v[232:235], v[2:5]
	s_setprio 0
	s_setprio 1
	v_mfma_f32_16x16x32_bf16 v[54:57], v[180:183], v[212:215], v[54:57]
	v_mfma_f32_16x16x32_bf16 v[50:53], v[204:207], v[212:215], v[50:53]
	v_mfma_f32_16x16x32_bf16 v[38:41], v[180:183], v[220:223], v[38:41]
	v_mfma_f32_16x16x32_bf16 v[34:37], v[204:207], v[220:223], v[34:37]
	v_mfma_f32_16x16x32_bf16 v[22:25], v[180:183], v[228:231], v[22:25]
	v_mfma_f32_16x16x32_bf16 v[18:21], v[204:207], v[228:231], v[18:21]
	v_mfma_f32_16x16x32_bf16 v[6:9], v[180:183], v[236:239], v[6:9]
	v_mfma_f32_16x16x32_bf16 v[2:5], v[204:207], v[236:239], v[2:5]
	s_setprio 0
	s_barrier
	s_add_i32 s76, 0, 0x18000
	s_add_i32 s77, 0, 0x1c000
	v_add_u32_e32 v172, s76, v1
	v_add_u32_e32 v203, s77, v1
	ds_read_b128 v[160:163], v172
	ds_read_b128 v[164:167], v172 offset:1024
	ds_read_b128 v[168:171], v172 offset:2048
	ds_read_b128 v[172:175], v172 offset:3072
	ds_read_b128 v[176:179], v203
	ds_read_b128 v[180:183], v203 offset:1024
	ds_read_b128 v[184:187], v203 offset:2048
	ds_read_b128 v[204:207], v203 offset:3072
	s_add_u32 s46, s62, 0x20000
	s_addc_u32 s47, s63, 0
	s_mov_b32 m0, s30
	v_lshl_add_u64 v[248:249], s[46:47], 0, v[150:151]
	ds_read_b128 v[208:211], v143 offset:32768
	ds_read_b128 v[212:215], v143 offset:33792
	ds_read_b128 v[216:219], v143 offset:34816
	ds_read_b128 v[220:223], v143 offset:35840
	ds_read_b128 v[224:227], v143 offset:36864
	ds_read_b128 v[228:231], v143 offset:37888
	ds_read_b128 v[232:235], v143 offset:38912
	ds_read_b128 v[236:239], v143 offset:39936
	global_load_lds_dwordx4 v[248:249], off
	v_lshl_add_u64 v[248:249], s[46:47], 0, v[146:147]
	s_mov_b32 m0, s34
	s_nop 0
	global_load_lds_dwordx4 v[248:249], off
	s_waitcnt vmcnt(8)
	s_waitcnt lgkmcnt(0)
	s_setprio 1
	s_barrier
	v_mfma_f32_16x16x32_bf16 v[126:129], v[160:163], v[208:211], v[126:129]
	v_mfma_f32_16x16x32_bf16 v[122:125], v[168:171], v[208:211], v[122:125]
	v_mfma_f32_16x16x32_bf16 v[110:113], v[160:163], v[216:219], v[110:113]
	v_mfma_f32_16x16x32_bf16 v[106:109], v[168:171], v[216:219], v[106:109]
	v_mfma_f32_16x16x32_bf16 v[94:97], v[160:163], v[224:227], v[94:97]
	v_mfma_f32_16x16x32_bf16 v[90:93], v[168:171], v[224:227], v[90:93]
	v_mfma_f32_16x16x32_bf16 v[78:81], v[160:163], v[232:235], v[78:81]
	v_mfma_f32_16x16x32_bf16 v[74:77], v[168:171], v[232:235], v[74:77]
	s_setprio 0
	s_setprio 1
	v_mfma_f32_16x16x32_bf16 v[126:129], v[164:167], v[212:215], v[126:129]
	v_mfma_f32_16x16x32_bf16 v[122:125], v[172:175], v[212:215], v[122:125]
	v_mfma_f32_16x16x32_bf16 v[110:113], v[164:167], v[220:223], v[110:113]
	v_mfma_f32_16x16x32_bf16 v[106:109], v[172:175], v[220:223], v[106:109]
	v_mfma_f32_16x16x32_bf16 v[94:97], v[164:167], v[228:231], v[94:97]
	v_mfma_f32_16x16x32_bf16 v[90:93], v[172:175], v[228:231], v[90:93]
	v_mfma_f32_16x16x32_bf16 v[78:81], v[164:167], v[236:239], v[78:81]
	v_mfma_f32_16x16x32_bf16 v[74:77], v[172:175], v[236:239], v[74:77]
	s_setprio 0
	s_setprio 1
	v_mfma_f32_16x16x32_bf16 v[118:121], v[176:179], v[208:211], v[118:121]
	v_mfma_f32_16x16x32_bf16 v[114:117], v[184:187], v[208:211], v[114:117]
	v_mfma_f32_16x16x32_bf16 v[102:105], v[176:179], v[216:219], v[102:105]
	v_mfma_f32_16x16x32_bf16 v[98:101], v[184:187], v[216:219], v[98:101]
	v_mfma_f32_16x16x32_bf16 v[86:89], v[176:179], v[224:227], v[86:89]
	v_mfma_f32_16x16x32_bf16 v[82:85], v[184:187], v[224:227], v[82:85]
	v_mfma_f32_16x16x32_bf16 v[70:73], v[176:179], v[232:235], v[70:73]
	v_mfma_f32_16x16x32_bf16 v[66:69], v[184:187], v[232:235], v[66:69]
	s_setprio 0
	s_setprio 1
	v_mfma_f32_16x16x32_bf16 v[118:121], v[180:183], v[212:215], v[118:121]
	v_mfma_f32_16x16x32_bf16 v[114:117], v[204:207], v[212:215], v[114:117]
	v_mfma_f32_16x16x32_bf16 v[102:105], v[180:183], v[220:223], v[102:105]
	v_mfma_f32_16x16x32_bf16 v[98:101], v[204:207], v[220:223], v[98:101]
	v_mfma_f32_16x16x32_bf16 v[86:89], v[180:183], v[228:231], v[86:89]
	v_mfma_f32_16x16x32_bf16 v[82:85], v[204:207], v[228:231], v[82:85]
	v_mfma_f32_16x16x32_bf16 v[70:73], v[180:183], v[236:239], v[70:73]
	v_mfma_f32_16x16x32_bf16 v[66:69], v[204:207], v[236:239], v[66:69]
	s_setprio 0
	s_barrier
; #define PG8_STAGE(bufoff, gbase, voff) do { _Pragma("unroll") for (int _i = 0; _i < 2; ++_i) \
;         __builtin_amdgcn_global_load_lds((const unsigned*)((const char*)(gbase) + (voff)[_i]), (PG8_LAS unsigned*)(lds + (bufoff) + ldsw + _i * 8192), 16, 0, 0); } while (0)
; #define PG8_LDA(dst, b, h) do { _Pragma("unroll") for (int m = 0; m < 4; ++m) _Pragma("unroll") for (int k = 0; k < 2; ++k) dst[m][k] = *(const PG8_LAS bf16x8*)(lds + PG8_SA(b, h) + aoff + m * 2048 + k * 1024); } while (0)
; #define PG8_MMA(ai, bj, At, Bt) do { __builtin_amdgcn_s_setprio(1); _Pragma("unroll") for (int m = 0; m < 4; ++m) _Pragma("unroll") for (int n = 0; n < 2; ++n) _Pragma("unroll") for (int k = 0; k < 2; ++k) \
;         acc[ai][bj][m][n] = __builtin_amdgcn_mfma_f32_16x16x32_bf16(Bt[n][k], At[m][k], acc[ai][bj][m][n], 0, 0, 0); __builtin_amdgcn_s_setprio(0); } while (0)
; #define PG8_WAIT_V(n) asm volatile("s_waitcnt vmcnt(" #n ")" ::: "memory")
; #define PG8_WAIT_L(n) asm volatile("s_waitcnt lgkmcnt(" #n ")" ::: "memory")
; #define PG8_BAR __builtin_amdgcn_s_barrier()
; #define PG8_SCHED __builtin_amdgcn_sched_barrier(0)
;     __device__ __forceinline__ void operator()(const f32x4 (&acc)[2][2][4][2], const Unit& u, int wr, int wc, int fr, int fq) const {
;         const int row0 = u.pm * BM + wr * 64 + fr, col0 = u.pn * BM + wc * 32 + 8 * fq;
;         const int tidn = (wr * 4 + wc) * 64 + fq * 16 + fr;
;         const u32x4* gp = (const u32x4*)G8 + (size_t)(u.pm * 16 + gsel + u.pn) * 8 * 512 + tidn;
;         u32x4* mp = M1 + (size_t)(u.pm * 8 + u.pn) * 16 * 512 + tidn;
;         constexpr float K255 = 1.0f / 255.0f;
; #pragma unroll
;         for (int ai = 0; ai < 2; ++ai)
; #pragma unroll
;             for (int m = 0; m < 4; ++m) { const size_t row = (size_t)(row0 + ai * HALF + m * 16);
;                 const u32x4 gw = gp[(ai * 4 + m) * 512];
; template <class Epi, class Sched, bool ALIGN_EPI = false, bool SP2 = false>
; __device__ __forceinline__ void gemm_phase(PG8_LAS unsigned char* lds, const Gemm g, const Sched& S, const Epi& E) {
;     ...
;             PG8_LDA(At, 1, 1); PG8_STAGE(PG8_SB(1, 0), b3, voffB); PG8_STAGE(PG8_SB(1, 1), b3 + hstep, voffB); PG8_STAGE(PG8_SA(1, 0), a3, voffA);
;             PG8_WAIT_V(8); PG8_WAIT_L(0); PG8_BAR; PG8_MMA(1, 0, At, B0); PG8_MMA(1, 1, At, B1); PG8_BAR; PG8_SCHED;
	s_add_i32 s46, s76, s4
	v_lshl_add_u64 v[240:241], v[240:241], 0, s[68:69]
	s_mov_b32 m0, s46
	ds_read_b128 v[208:211], v143 offset:49152
	ds_read_b128 v[212:215], v143 offset:50176
	ds_read_b128 v[216:219], v143 offset:51200
	ds_read_b128 v[220:223], v143 offset:52224
	ds_read_b128 v[224:227], v143 offset:53248
	ds_read_b128 v[228:231], v143 offset:54272
	ds_read_b128 v[232:235], v143 offset:55296
	ds_read_b128 v[236:239], v143 offset:56320
	global_load_lds_dwordx4 v[240:241], off
	s_add_i32 m0, s46, 0x2000
	s_add_u32 s18, s18, 0x20080
	v_lshl_add_u64 v[240:241], v[242:243], 0, s[68:69]
	s_addc_u32 s19, s19, 0
	s_add_i32 s46, s77, s4
	global_load_lds_dwordx4 v[240:241], off
	v_lshl_add_u64 v[240:241], s[18:19], 0, v[148:149]
	s_mov_b32 m0, s46
	s_nop 0
	global_load_lds_dwordx4 v[240:241], off
	v_lshl_add_u64 v[240:241], s[18:19], 0, v[144:145]
	s_add_i32 m0, s46, 0x2000
	s_nop 0
	global_load_lds_dwordx4 v[240:241], off
	v_lshl_add_u64 v[240:241], v[244:245], 0, s[68:69]
	s_mov_b32 m0, s54
	s_nop 0
	global_load_lds_dwordx4 v[240:241], off
	v_lshl_add_u64 v[240:241], v[246:247], 0, s[68:69]
	s_mov_b32 m0, s57
	s_nop 0
	global_load_lds_dwordx4 v[240:241], off
	s_nop 0
	s_waitcnt vmcnt(8)
	s_waitcnt lgkmcnt(0)
	s_setprio 1
	s_barrier
	v_mfma_f32_16x16x32_bf16 v[62:65], v[160:163], v[208:211], v[62:65]
	v_mfma_f32_16x16x32_bf16 v[58:61], v[168:171], v[208:211], v[58:61]
	v_mfma_f32_16x16x32_bf16 v[46:49], v[160:163], v[216:219], v[46:49]
	v_mfma_f32_16x16x32_bf16 v[42:45], v[168:171], v[216:219], v[42:45]
	v_mfma_f32_16x16x32_bf16 v[30:33], v[160:163], v[224:227], v[30:33]
	v_mfma_f32_16x16x32_bf16 v[26:29], v[168:171], v[224:227], v[26:29]
	v_mfma_f32_16x16x32_bf16 v[14:17], v[160:163], v[232:235], v[14:17]
	v_mfma_f32_16x16x32_bf16 v[10:13], v[168:171], v[232:235], v[10:13]
	s_setprio 0
	s_setprio 1
	v_mfma_f32_16x16x32_bf16 v[62:65], v[164:167], v[212:215], v[62:65]
	v_mfma_f32_16x16x32_bf16 v[58:61], v[172:175], v[212:215], v[58:61]
	v_mfma_f32_16x16x32_bf16 v[46:49], v[164:167], v[220:223], v[46:49]
	v_mfma_f32_16x16x32_bf16 v[42:45], v[172:175], v[220:223], v[42:45]
	v_mfma_f32_16x16x32_bf16 v[30:33], v[164:167], v[228:231], v[30:33]
	v_mfma_f32_16x16x32_bf16 v[26:29], v[172:175], v[228:231], v[26:29]
	v_mfma_f32_16x16x32_bf16 v[14:17], v[164:167], v[236:239], v[14:17]
	v_mfma_f32_16x16x32_bf16 v[10:13], v[172:175], v[236:239], v[10:13]
	s_setprio 0
	s_setprio 1
	v_mfma_f32_16x16x32_bf16 v[54:57], v[176:179], v[208:211], v[54:57]
	v_mfma_f32_16x16x32_bf16 v[50:53], v[184:187], v[208:211], v[50:53]
	v_mfma_f32_16x16x32_bf16 v[38:41], v[176:179], v[216:219], v[38:41]
	v_mfma_f32_16x16x32_bf16 v[34:37], v[184:187], v[216:219], v[34:37]
	v_mfma_f32_16x16x32_bf16 v[22:25], v[176:179], v[224:227], v[22:25]
	v_mfma_f32_16x16x32_bf16 v[18:21], v[184:187], v[224:227], v[18:21]
	v_mfma_f32_16x16x32_bf16 v[6:9], v[176:179], v[232:235], v[6:9]
	v_mfma_f32_16x16x32_bf16 v[2:5], v[184:187], v[232:235], v[2:5]
	s_setprio 0
	s_setprio 1
	v_mfma_f32_16x16x32_bf16 v[54:57], v[180:183], v[212:215], v[54:57]
	v_mfma_f32_16x16x32_bf16 v[50:53], v[204:207], v[212:215], v[50:53]
	v_mfma_f32_16x16x32_bf16 v[38:41], v[180:183], v[220:223], v[38:41]
	v_mfma_f32_16x16x32_bf16 v[34:37], v[204:207], v[220:223], v[34:37]
	v_mfma_f32_16x16x32_bf16 v[22:25], v[180:183], v[228:231], v[22:25]
	v_mfma_f32_16x16x32_bf16 v[18:21], v[204:207], v[228:231], v[18:21]
	v_mfma_f32_16x16x32_bf16 v[6:9], v[180:183], v[236:239], v[6:9]
	v_mfma_f32_16x16x32_bf16 v[2:5], v[204:207], v[236:239], v[2:5]
	s_setprio 0
	s_barrier
	s_add_i32 s79, s79, 2
	s_add_u32 s58, s58, 0x100
	s_addc_u32 s59, s59, 0
	s_add_u32 s85, s85, 0x100
	s_addc_u32 s78, s78, 0
	s_cmp_gt_u32 s79, 5
	s_cbranch_scc0 .LBB0_136
	s_lshl_b32 s11, s67, 4
	s_add_i32 s18, s11, s86
	s_ashr_i32 s19, s18, 31
	s_lshl_b64 s[46:47], s[18:19], 16
	v_lshl_add_u64 v[162:163], v[152:153], 0, s[46:47]
	s_lshl_b32 s11, s67, 3
	s_sub_i32 s18, s18, s11
	s_ashr_i32 s19, s18, 31
	s_lshl_b64 s[18:19], s[18:19], 17
	v_lshl_add_u64 v[160:161], v[154:155], 0, s[18:19]
	s_mov_b32 s47, 0
	global_load_dwordx4 v[168:171], v[162:163], off
	s_mov_b32 s46, 0x2000
	v_lshl_add_u64 v[164:165], v[162:163], 0, s[46:47]
	global_load_dwordx4 v[172:175], v[164:165], off
	s_mov_b32 s46, 0x4000
	v_lshl_add_u64 v[164:165], v[162:163], 0, s[46:47]
	global_load_dwordx4 v[176:179], v[164:165], off
	s_mov_b32 s46, 0x6000
	v_lshl_add_u64 v[164:165], v[162:163], 0, s[46:47]
	global_load_dwordx4 v[180:183], v[164:165], off
	s_mov_b32 s46, 0x8000
	v_lshl_add_u64 v[164:165], v[162:163], 0, s[46:47]
	global_load_dwordx4 v[184:187], v[164:165], off
	s_mov_b32 s46, 0xa000
	v_lshl_add_u64 v[164:165], v[162:163], 0, s[46:47]
	global_load_dwordx4 v[204:207], v[164:165], off
	s_mov_b32 s46, 0xc000
	v_lshl_add_u64 v[164:165], v[162:163], 0, s[46:47]
	global_load_dwordx4 v[208:211], v[164:165], off
	s_mov_b32 s46, 0xe000
	v_lshl_add_u64 v[164:165], v[162:163], 0, s[46:47]
	global_load_dwordx4 v[212:215], v[164:165], off
	s_and_b64 vcc, exec, s[8:9]
	s_cbranch_vccz .Lg0_nobar
	s_barrier

; #define PG8_STAGE(bufoff, gbase, voff) do { _Pragma("unroll") for (int _i = 0; _i < 2; ++_i) \
;         __builtin_amdgcn_global_load_lds((const unsigned*)((const char*)(gbase) + (voff)[_i]), (PG8_LAS unsigned*)(lds + (bufoff) + ldsw + _i * 8192), 16, 0, 0); } while (0)
; #define PG8_LDA(dst, b, h) do { _Pragma("unroll") for (int m = 0; m < 4; ++m) _Pragma("unroll") for (int k = 0; k < 2; ++k) dst[m][k] = *(const PG8_LAS bf16x8*)(lds + PG8_SA(b, h) + aoff + m * 2048 + k * 1024); } while (0)
; #define PG8_LDB(dst, b, h) do { _Pragma("unroll") for (int n = 0; n < 2; ++n) _Pragma("unroll") for (int k = 0; k < 2; ++k) dst[n][k] = *(const PG8_LAS bf16x8*)(lds + PG8_SB(b, h) + boff + n * 2048 + k * 1024); } while (0)
; #define PG8_WAIT_V(n) asm volatile("s_waitcnt vmcnt(" #n ")" ::: "memory")
; #define PG8_WAIT_L(n) asm volatile("s_waitcnt lgkmcnt(" #n ")" ::: "memory")
; #define PG8_BAR __builtin_amdgcn_s_barrier()
; #define PG8_SCHED __builtin_amdgcn_sched_barrier(0)
; template <class Epi, class Sched, bool ALIGN_EPI = false, bool SP2 = false>
; __device__ __forceinline__ void gemm_phase(PG8_LAS unsigned char* lds, const Gemm g, const Sched& S, const Epi& E) {
;     ...
;         const char* nA = has_next ? (const char*)g.A + (size_t)nxt.pm * tstep : cA; const char* nB = has_next ? (const char*)g.Bt + (size_t)nxt.pn * tstep : cB;
;         for (int t = 0; t < nt; t += 2) {
;             const bool last = (t == nt - 2);
;             const char* a1 = cA + (size_t)(t + 1) * kstep;
;             const char* a2 = last ? nA : cA + (size_t)(t + 2) * kstep; const char* b2 = last ? nB : cB + (size_t)(t + 2) * kstep;
;             const char* a3 = a2 + kstep; const char* b3 = b2 + kstep;
;             if (last && has_next) S.a_ready(nxt);
;             if constexpr (SP2) {
;             PG8_LDB(B0, 0, 0); PG8_LDB(B1, 0, 1); PG8_SCHED; PG8_LDA(At, 0, 0); PG8_STAGE(PG8_SA(1, 1), a1 + hstep, voffA);
;             PG8_WAIT_V(8); PG8_WAIT_L(0); PG8_BAR; PG8_MMA(0, 0, At, B0); PG8_MMA(0, 1, At, B1); PG8_BAR; PG8_SCHED;
;             PG8_LDA(At, 0, 1); PG8_STAGE(PG8_SB(0, 0), b2, voffB); PG8_STAGE(PG8_SB(0, 1), b2 + hstep, voffB); PG8_STAGE(PG8_SA(0, 0), a2, voffA);
;             PG8_WAIT_V(8); PG8_WAIT_L(0); PG8_BAR; PG8_MMA(1, 0, At, B0); PG8_MMA(1, 1, At, B1); PG8_BAR; PG8_SCHED;
.LBB0_160:
	s_add_u32 s42, s36, 0x100
	s_addc_u32 s43, s37, 0
	s_add_i32 s47, 0, 0x10000
	s_cmp_eq_u32 s46, 20
	s_cselect_b32 s45, s1, s43
	s_cselect_b32 s44, s0, s42
	s_cselect_b32 s19, s7, s73
	s_cselect_b32 s18, s6, s60
	s_add_i32 s76, 0, 0x14000
	v_add_u32_e32 v174, s47, v143
	v_add_u32_e32 v186, s76, v143
	ds_read_b128 v[160:163], v174
	ds_read_b128 v[164:167], v174 offset:1024
	ds_read_b128 v[170:173], v174 offset:2048
	ds_read_b128 v[174:177], v174 offset:3072
	ds_read_b128 v[178:181], v186
	ds_read_b128 v[182:185], v186 offset:1024
	ds_read_b128 v[204:207], v186 offset:2048
	ds_read_b128 v[208:211], v186 offset:3072
	v_lshl_add_u64 v[186:187], s[36:37], 0, v[156:157]
	s_add_i32 m0, s54, 0xc000
	ds_read_b128 v[212:215], v169
	ds_read_b128 v[216:219], v169 offset:1024
	ds_read_b128 v[220:223], v169 offset:2048
	ds_read_b128 v[224:227], v169 offset:3072
	ds_read_b128 v[228:231], v169 offset:4096
	ds_read_b128 v[232:235], v169 offset:5120
	ds_read_b128 v[236:239], v169 offset:6144
	ds_read_b128 v[240:243], v169 offset:7168
	global_load_lds_dwordx4 v[186:187], off
	v_lshl_add_u64 v[186:187], s[36:37], 0, v[158:159]
	s_add_i32 m0, s54, 0xe000
	s_nop 0
	global_load_lds_dwordx4 v[186:187], off
	s_waitcnt vmcnt(8)
	s_waitcnt lgkmcnt(0)
	s_setprio 1
	s_barrier
	v_mfma_f32_16x16x32_bf16 v[126:129], v[160:163], v[212:215], v[126:129]
	v_mfma_f32_16x16x32_bf16 v[122:125], v[170:173], v[212:215], v[122:125]
	v_mfma_f32_16x16x32_bf16 v[110:113], v[160:163], v[220:223], v[110:113]
	v_mfma_f32_16x16x32_bf16 v[106:109], v[170:173], v[220:223], v[106:109]
	v_mfma_f32_16x16x32_bf16 v[94:97], v[160:163], v[228:231], v[94:97]
	v_mfma_f32_16x16x32_bf16 v[90:93], v[170:173], v[228:231], v[90:93]
	v_mfma_f32_16x16x32_bf16 v[78:81], v[160:163], v[236:239], v[78:81]
	v_mfma_f32_16x16x32_bf16 v[74:77], v[170:173], v[236:239], v[74:77]
	s_setprio 0
	s_setprio 1
	v_mfma_f32_16x16x32_bf16 v[126:129], v[164:167], v[216:219], v[126:129]
	v_mfma_f32_16x16x32_bf16 v[122:125], v[174:177], v[216:219], v[122:125]
	v_mfma_f32_16x16x32_bf16 v[110:113], v[164:167], v[224:227], v[110:113]
	v_mfma_f32_16x16x32_bf16 v[106:109], v[174:177], v[224:227], v[106:109]
	v_mfma_f32_16x16x32_bf16 v[94:97], v[164:167], v[232:235], v[94:97]
	v_mfma_f32_16x16x32_bf16 v[90:93], v[174:177], v[232:235], v[90:93]
	v_mfma_f32_16x16x32_bf16 v[78:81], v[164:167], v[240:243], v[78:81]
	v_mfma_f32_16x16x32_bf16 v[74:77], v[174:177], v[240:243], v[74:77]
	s_setprio 0
	s_setprio 1
	v_mfma_f32_16x16x32_bf16 v[118:121], v[178:181], v[212:215], v[118:121]
	v_mfma_f32_16x16x32_bf16 v[114:117], v[204:207], v[212:215], v[114:117]
	v_mfma_f32_16x16x32_bf16 v[102:105], v[178:181], v[220:223], v[102:105]
	v_mfma_f32_16x16x32_bf16 v[98:101], v[204:207], v[220:223], v[98:101]
	v_mfma_f32_16x16x32_bf16 v[86:89], v[178:181], v[228:231], v[86:89]
	v_mfma_f32_16x16x32_bf16 v[82:85], v[204:207], v[228:231], v[82:85]
	v_mfma_f32_16x16x32_bf16 v[70:73], v[178:181], v[236:239], v[70:73]
	v_mfma_f32_16x16x32_bf16 v[66:69], v[204:207], v[236:239], v[66:69]
	s_setprio 0
	s_setprio 1
	v_mfma_f32_16x16x32_bf16 v[118:121], v[182:185], v[216:219], v[118:121]
	v_mfma_f32_16x16x32_bf16 v[114:117], v[208:211], v[216:219], v[114:117]
	v_mfma_f32_16x16x32_bf16 v[102:105], v[182:185], v[224:227], v[102:105]
	v_mfma_f32_16x16x32_bf16 v[98:101], v[208:211], v[224:227], v[98:101]
	v_mfma_f32_16x16x32_bf16 v[86:89], v[182:185], v[232:235], v[86:89]
	v_mfma_f32_16x16x32_bf16 v[82:85], v[208:211], v[232:235], v[82:85]
	v_mfma_f32_16x16x32_bf16 v[70:73], v[182:185], v[240:243], v[70:73]
	v_mfma_f32_16x16x32_bf16 v[66:69], v[208:211], v[240:243], v[66:69]
	s_setprio 0
	s_barrier
	s_add_i32 s36, s47, s4
	v_lshl_add_u64 v[186:187], s[18:19], 0, v[148:149]
	s_mov_b32 m0, s36
	ds_read_b128 v[212:215], v169 offset:16384
	ds_read_b128 v[216:219], v169 offset:17408
	ds_read_b128 v[220:223], v169 offset:18432
	ds_read_b128 v[224:227], v169 offset:19456
	ds_read_b128 v[228:231], v169 offset:20480
	ds_read_b128 v[232:235], v169 offset:21504
	ds_read_b128 v[236:239], v169 offset:22528
	ds_read_b128 v[240:243], v169 offset:23552
	global_load_lds_dwordx4 v[186:187], off
	s_add_i32 m0, s36, 0x2000
	s_add_u32 s36, s18, 0x60000
	v_lshl_add_u64 v[244:245], s[18:19], 0, v[144:145]
	s_addc_u32 s37, s19, 0
	s_add_i32 s47, s76, s4
	global_load_lds_dwordx4 v[244:245], off
	v_lshl_add_u64 v[246:247], s[36:37], 0, v[148:149]
	s_mov_b32 m0, s47
	v_lshl_add_u64 v[248:249], s[44:45], 0, v[146:147]
	global_load_lds_dwordx4 v[246:247], off
	v_lshl_add_u64 v[246:247], s[36:37], 0, v[144:145]
	s_add_i32 m0, s47, 0x2000
	s_nop 0
	global_load_lds_dwordx4 v[246:247], off
	v_lshl_add_u64 v[246:247], s[44:45], 0, v[150:151]
	s_mov_b32 m0, s54
	s_nop 0
	global_load_lds_dwordx4 v[246:247], off
	s_mov_b32 m0, s57
	s_nop 0
	global_load_lds_dwordx4 v[248:249], off
	s_waitcnt vmcnt(8)
	s_waitcnt lgkmcnt(0)
	s_setprio 1
	s_barrier
; #define PG8_STAGE(bufoff, gbase, voff) do { _Pragma("unroll") for (int _i = 0; _i < 2; ++_i) \
;         __builtin_amdgcn_global_load_lds((const unsigned*)((const char*)(gbase) + (voff)[_i]), (PG8_LAS unsigned*)(lds + (bufoff) + ldsw + _i * 8192), 16, 0, 0); } while (0)
; #define PG8_LDA(dst, b, h) do { _Pragma("unroll") for (int m = 0; m < 4; ++m) _Pragma("unroll") for (int k = 0; k < 2; ++k) dst[m][k] = *(const PG8_LAS bf16x8*)(lds + PG8_SA(b, h) + aoff + m * 2048 + k * 1024); } while (0)
; #define PG8_LDB(dst, b, h) do { _Pragma("unroll") for (int n = 0; n < 2; ++n) _Pragma("unroll") for (int k = 0; k < 2; ++k) dst[n][k] = *(const PG8_LAS bf16x8*)(lds + PG8_SB(b, h) + boff + n * 2048 + k * 1024); } while (0)
; #define PG8_MMA(ai, bj, At, Bt) do { __builtin_amdgcn_s_setprio(1); _Pragma("unroll") for (int m = 0; m < 4; ++m) _Pragma("unroll") for (int n = 0; n < 2; ++n) _Pragma("unroll") for (int k = 0; k < 2; ++k) \
;         acc[ai][bj][m][n] = __builtin_amdgcn_mfma_f32_16x16x32_bf16(Bt[n][k], At[m][k], acc[ai][bj][m][n], 0, 0, 0); __builtin_amdgcn_s_setprio(0); } while (0)
; #define PG8_WAIT_V(n) asm volatile("s_waitcnt vmcnt(" #n ")" ::: "memory")
; #define PG8_WAIT_L(n) asm volatile("s_waitcnt lgkmcnt(" #n ")" ::: "memory")
; #define PG8_BAR __builtin_amdgcn_s_barrier()
; #define PG8_SCHED __builtin_amdgcn_sched_barrier(0)
; template <class Epi, class Sched, bool ALIGN_EPI = false, bool SP2 = false>
; __device__ __forceinline__ void gemm_phase(PG8_LAS unsigned char* lds, const Gemm g, const Sched& S, const Epi& E) {
;     ...
;             PG8_WAIT_V(8); PG8_WAIT_L(0); PG8_BAR; PG8_MMA(1, 0, At, B0); PG8_MMA(1, 1, At, B1); PG8_BAR; PG8_SCHED;
;             PG8_LDB(B0, 1, 0); PG8_LDB(B1, 1, 1); PG8_SCHED; PG8_LDA(At, 1, 0); PG8_STAGE(PG8_SA(0, 1), a2 + hstep, voffA);
;             PG8_WAIT_V(8); PG8_WAIT_L(0); PG8_BAR; PG8_MMA(0, 0, At, B0); PG8_MMA(0, 1, At, B1); PG8_BAR; PG8_SCHED;
	v_mfma_f32_16x16x32_bf16 v[62:65], v[160:163], v[212:215], v[62:65]
	v_mfma_f32_16x16x32_bf16 v[58:61], v[170:173], v[212:215], v[58:61]
	v_mfma_f32_16x16x32_bf16 v[46:49], v[160:163], v[220:223], v[46:49]
	v_mfma_f32_16x16x32_bf16 v[42:45], v[170:173], v[220:223], v[42:45]
	v_mfma_f32_16x16x32_bf16 v[30:33], v[160:163], v[228:231], v[30:33]
	v_mfma_f32_16x16x32_bf16 v[26:29], v[170:173], v[228:231], v[26:29]
	v_mfma_f32_16x16x32_bf16 v[14:17], v[160:163], v[236:239], v[14:17]
	v_mfma_f32_16x16x32_bf16 v[10:13], v[170:173], v[236:239], v[10:13]
	s_setprio 0
	s_setprio 1
	v_mfma_f32_16x16x32_bf16 v[62:65], v[164:167], v[216:219], v[62:65]
	v_mfma_f32_16x16x32_bf16 v[58:61], v[174:177], v[216:219], v[58:61]
	v_mfma_f32_16x16x32_bf16 v[46:49], v[164:167], v[224:227], v[46:49]
	v_mfma_f32_16x16x32_bf16 v[42:45], v[174:177], v[224:227], v[42:45]
	v_mfma_f32_16x16x32_bf16 v[30:33], v[164:167], v[232:235], v[30:33]
	v_mfma_f32_16x16x32_bf16 v[26:29], v[174:177], v[232:235], v[26:29]
	v_mfma_f32_16x16x32_bf16 v[14:17], v[164:167], v[240:243], v[14:17]
	v_mfma_f32_16x16x32_bf16 v[10:13], v[174:177], v[240:243], v[10:13]
	s_setprio 0
	s_setprio 1
	v_mfma_f32_16x16x32_bf16 v[54:57], v[178:181], v[212:215], v[54:57]
	v_mfma_f32_16x16x32_bf16 v[50:53], v[204:207], v[212:215], v[50:53]
	v_mfma_f32_16x16x32_bf16 v[38:41], v[178:181], v[220:223], v[38:41]
	v_mfma_f32_16x16x32_bf16 v[34:37], v[204:207], v[220:223], v[34:37]
	v_mfma_f32_16x16x32_bf16 v[22:25], v[178:181], v[228:231], v[22:25]
	v_mfma_f32_16x16x32_bf16 v[18:21], v[204:207], v[228:231], v[18:21]
	v_mfma_f32_16x16x32_bf16 v[6:9], v[178:181], v[236:239], v[6:9]
	v_mfma_f32_16x16x32_bf16 v[2:5], v[204:207], v[236:239], v[2:5]
	s_setprio 0
	s_setprio 1
	v_mfma_f32_16x16x32_bf16 v[54:57], v[182:185], v[216:219], v[54:57]
	v_mfma_f32_16x16x32_bf16 v[50:53], v[208:211], v[216:219], v[50:53]
	v_mfma_f32_16x16x32_bf16 v[38:41], v[182:185], v[224:227], v[38:41]
	v_mfma_f32_16x16x32_bf16 v[34:37], v[208:211], v[224:227], v[34:37]
	v_mfma_f32_16x16x32_bf16 v[22:25], v[182:185], v[232:235], v[22:25]
	v_mfma_f32_16x16x32_bf16 v[18:21], v[208:211], v[232:235], v[18:21]
	v_mfma_f32_16x16x32_bf16 v[6:9], v[182:185], v[240:243], v[6:9]
	v_mfma_f32_16x16x32_bf16 v[2:5], v[208:211], v[240:243], v[2:5]
	s_setprio 0
	s_barrier
	s_add_i32 s47, 0, 0x18000
	s_add_i32 s76, 0, 0x1c000
	v_add_u32_e32 v174, s47, v143
	v_add_u32_e32 v203, s76, v143
	ds_read_b128 v[160:163], v174
	ds_read_b128 v[164:167], v174 offset:1024
	ds_read_b128 v[170:173], v174 offset:2048
	ds_read_b128 v[174:177], v174 offset:3072
	ds_read_b128 v[178:181], v203
	ds_read_b128 v[182:185], v203 offset:1024
	ds_read_b128 v[204:207], v203 offset:2048
	ds_read_b128 v[208:211], v203 offset:3072
	s_add_u32 s36, s44, 0x60000
	s_addc_u32 s37, s45, 0
	s_mov_b32 m0, s58
	v_lshl_add_u64 v[250:251], s[36:37], 0, v[150:151]
	ds_read_b128 v[212:215], v169 offset:32768
	ds_read_b128 v[216:219], v169 offset:33792
	ds_read_b128 v[220:223], v169 offset:34816
	ds_read_b128 v[224:227], v169 offset:35840
	ds_read_b128 v[228:231], v169 offset:36864
	ds_read_b128 v[232:235], v169 offset:37888
	ds_read_b128 v[236:239], v169 offset:38912
	ds_read_b128 v[240:243], v169 offset:39936
	global_load_lds_dwordx4 v[250:251], off
	v_lshl_add_u64 v[250:251], s[36:37], 0, v[146:147]
	s_mov_b32 m0, s59
	s_nop 0
	global_load_lds_dwordx4 v[250:251], off
	s_waitcnt vmcnt(8)
	s_waitcnt lgkmcnt(0)
	s_setprio 1
	s_barrier
	v_mfma_f32_16x16x32_bf16 v[126:129], v[160:163], v[212:215], v[126:129]
	v_mfma_f32_16x16x32_bf16 v[122:125], v[170:173], v[212:215], v[122:125]
	v_mfma_f32_16x16x32_bf16 v[110:113], v[160:163], v[220:223], v[110:113]
	v_mfma_f32_16x16x32_bf16 v[106:109], v[170:173], v[220:223], v[106:109]
	v_mfma_f32_16x16x32_bf16 v[94:97], v[160:163], v[228:231], v[94:97]
	v_mfma_f32_16x16x32_bf16 v[90:93], v[170:173], v[228:231], v[90:93]
	v_mfma_f32_16x16x32_bf16 v[78:81], v[160:163], v[236:239], v[78:81]
	v_mfma_f32_16x16x32_bf16 v[74:77], v[170:173], v[236:239], v[74:77]
	s_setprio 0
	s_setprio 1
	v_mfma_f32_16x16x32_bf16 v[126:129], v[164:167], v[216:219], v[126:129]
	v_mfma_f32_16x16x32_bf16 v[122:125], v[174:177], v[216:219], v[122:125]
	v_mfma_f32_16x16x32_bf16 v[110:113], v[164:167], v[224:227], v[110:113]
	v_mfma_f32_16x16x32_bf16 v[106:109], v[174:177], v[224:227], v[106:109]
	v_mfma_f32_16x16x32_bf16 v[94:97], v[164:167], v[232:235], v[94:97]
	v_mfma_f32_16x16x32_bf16 v[90:93], v[174:177], v[232:235], v[90:93]
	v_mfma_f32_16x16x32_bf16 v[78:81], v[164:167], v[240:243], v[78:81]
	v_mfma_f32_16x16x32_bf16 v[74:77], v[174:177], v[240:243], v[74:77]
	s_setprio 0
	s_setprio 1
	v_mfma_f32_16x16x32_bf16 v[118:121], v[178:181], v[212:215], v[118:121]
	v_mfma_f32_16x16x32_bf16 v[114:117], v[204:207], v[212:215], v[114:117]
	v_mfma_f32_16x16x32_bf16 v[102:105], v[178:181], v[220:223], v[102:105]
	v_mfma_f32_16x16x32_bf16 v[98:101], v[204:207], v[220:223], v[98:101]
	v_mfma_f32_16x16x32_bf16 v[86:89], v[178:181], v[228:231], v[86:89]
	v_mfma_f32_16x16x32_bf16 v[82:85], v[204:207], v[228:231], v[82:85]
	v_mfma_f32_16x16x32_bf16 v[70:73], v[178:181], v[236:239], v[70:73]
	v_mfma_f32_16x16x32_bf16 v[66:69], v[204:207], v[236:239], v[66:69]
	s_setprio 0
	s_setprio 1
	v_mfma_f32_16x16x32_bf16 v[118:121], v[182:185], v[216:219], v[118:121]
	v_mfma_f32_16x16x32_bf16 v[114:117], v[208:211], v[216:219], v[114:117]
	v_mfma_f32_16x16x32_bf16 v[102:105], v[182:185], v[224:227], v[102:105]
	v_mfma_f32_16x16x32_bf16 v[98:101], v[208:211], v[224:227], v[98:101]
	v_mfma_f32_16x16x32_bf16 v[86:89], v[182:185], v[232:235], v[86:89]
	v_mfma_f32_16x16x32_bf16 v[82:85], v[208:211], v[232:235], v[82:85]
	v_mfma_f32_16x16x32_bf16 v[70:73], v[182:185], v[240:243], v[70:73]
	v_mfma_f32_16x16x32_bf16 v[66:69], v[208:211], v[240:243], v[66:69]
	s_setprio 0
	s_barrier
; #define PG8_STAGE(bufoff, gbase, voff) do { _Pragma("unroll") for (int _i = 0; _i < 2; ++_i) \
;         __builtin_amdgcn_global_load_lds((const unsigned*)((const char*)(gbase) + (voff)[_i]), (PG8_LAS unsigned*)(lds + (bufoff) + ldsw + _i * 8192), 16, 0, 0); } while (0)
; #define PG8_LDA(dst, b, h) do { _Pragma("unroll") for (int m = 0; m < 4; ++m) _Pragma("unroll") for (int k = 0; k < 2; ++k) dst[m][k] = *(const PG8_LAS bf16x8*)(lds + PG8_SA(b, h) + aoff + m * 2048 + k * 1024); } while (0)
; #define PG8_MMA(ai, bj, At, Bt) do { __builtin_amdgcn_s_setprio(1); _Pragma("unroll") for (int m = 0; m < 4; ++m) _Pragma("unroll") for (int n = 0; n < 2; ++n) _Pragma("unroll") for (int k = 0; k < 2; ++k) \
;         acc[ai][bj][m][n] = __builtin_amdgcn_mfma_f32_16x16x32_bf16(Bt[n][k], At[m][k], acc[ai][bj][m][n], 0, 0, 0); __builtin_amdgcn_s_setprio(0); } while (0)
; #define PG8_WAIT_V(n) asm volatile("s_waitcnt vmcnt(" #n ")" ::: "memory")
; #define PG8_WAIT_L(n) asm volatile("s_waitcnt lgkmcnt(" #n ")" ::: "memory")
; #define PG8_BAR __builtin_amdgcn_s_barrier()
; #define PG8_SCHED __builtin_amdgcn_sched_barrier(0)
; template <class Epi, class Sched, bool ALIGN_EPI = false, bool SP2 = false>
; __device__ __forceinline__ void gemm_phase(PG8_LAS unsigned char* lds, const Gemm g, const Sched& S, const Epi& E) {
;     ...
;             PG8_LDA(At, 1, 1); PG8_STAGE(PG8_SB(1, 0), b3, voffB); PG8_STAGE(PG8_SB(1, 1), b3 + hstep, voffB); PG8_STAGE(PG8_SA(1, 0), a3, voffA);
;             PG8_WAIT_V(8); PG8_WAIT_L(0); PG8_BAR; PG8_MMA(1, 0, At, B0); PG8_MMA(1, 1, At, B1); PG8_BAR; PG8_SCHED;
;     ...
;         if constexpr (ALIGN_EPI) { if (wr == 0) PG8_BAR; }
	s_add_i32 s36, s47, s4
	v_lshl_add_u64 v[186:187], v[186:187], 0, s[68:69]
	s_mov_b32 m0, s36
	ds_read_b128 v[212:215], v169 offset:49152
	ds_read_b128 v[216:219], v169 offset:50176
	ds_read_b128 v[220:223], v169 offset:51200
	ds_read_b128 v[224:227], v169 offset:52224
	ds_read_b128 v[228:231], v169 offset:53248
	ds_read_b128 v[232:235], v169 offset:54272
	ds_read_b128 v[236:239], v169 offset:55296
	ds_read_b128 v[240:243], v169 offset:56320
	global_load_lds_dwordx4 v[186:187], off
	s_add_i32 m0, s36, 0x2000
	s_add_u32 s18, s18, 0x60080
	v_lshl_add_u64 v[186:187], v[244:245], 0, s[68:69]
	s_addc_u32 s19, s19, 0
	s_add_i32 s36, s76, s4
	global_load_lds_dwordx4 v[186:187], off
	v_lshl_add_u64 v[186:187], s[18:19], 0, v[148:149]
	s_mov_b32 m0, s36
	s_nop 0
	global_load_lds_dwordx4 v[186:187], off
	v_lshl_add_u64 v[186:187], s[18:19], 0, v[144:145]
	s_add_i32 m0, s36, 0x2000
	s_nop 0
	global_load_lds_dwordx4 v[186:187], off
	v_lshl_add_u64 v[186:187], v[246:247], 0, s[68:69]
	s_mov_b32 m0, s62
	s_nop 0
	global_load_lds_dwordx4 v[186:187], off
	v_lshl_add_u64 v[186:187], v[248:249], 0, s[68:69]
	s_mov_b32 m0, s63
	s_nop 0
	global_load_lds_dwordx4 v[186:187], off
	s_nop 0
	s_waitcnt vmcnt(8)
	s_waitcnt lgkmcnt(0)
	s_setprio 1
	s_barrier
	v_mfma_f32_16x16x32_bf16 v[62:65], v[160:163], v[212:215], v[62:65]
	v_mfma_f32_16x16x32_bf16 v[58:61], v[170:173], v[212:215], v[58:61]
	v_mfma_f32_16x16x32_bf16 v[46:49], v[160:163], v[220:223], v[46:49]
	v_mfma_f32_16x16x32_bf16 v[42:45], v[170:173], v[220:223], v[42:45]
	v_mfma_f32_16x16x32_bf16 v[30:33], v[160:163], v[228:231], v[30:33]
	v_mfma_f32_16x16x32_bf16 v[26:29], v[170:173], v[228:231], v[26:29]
	v_mfma_f32_16x16x32_bf16 v[14:17], v[160:163], v[236:239], v[14:17]
	v_mfma_f32_16x16x32_bf16 v[10:13], v[170:173], v[236:239], v[10:13]
	s_setprio 0
	s_setprio 1
	v_mfma_f32_16x16x32_bf16 v[62:65], v[164:167], v[216:219], v[62:65]
	v_mfma_f32_16x16x32_bf16 v[58:61], v[174:177], v[216:219], v[58:61]
	v_mfma_f32_16x16x32_bf16 v[46:49], v[164:167], v[224:227], v[46:49]
	v_mfma_f32_16x16x32_bf16 v[42:45], v[174:177], v[224:227], v[42:45]
	v_mfma_f32_16x16x32_bf16 v[30:33], v[164:167], v[232:235], v[30:33]
	v_mfma_f32_16x16x32_bf16 v[26:29], v[174:177], v[232:235], v[26:29]
	v_mfma_f32_16x16x32_bf16 v[14:17], v[164:167], v[240:243], v[14:17]
	v_mfma_f32_16x16x32_bf16 v[10:13], v[174:177], v[240:243], v[10:13]
	s_setprio 0
	s_setprio 1
	v_mfma_f32_16x16x32_bf16 v[54:57], v[178:181], v[212:215], v[54:57]
	v_mfma_f32_16x16x32_bf16 v[50:53], v[204:207], v[212:215], v[50:53]
	v_mfma_f32_16x16x32_bf16 v[38:41], v[178:181], v[220:223], v[38:41]
	v_mfma_f32_16x16x32_bf16 v[34:37], v[204:207], v[220:223], v[34:37]
	v_mfma_f32_16x16x32_bf16 v[22:25], v[178:181], v[228:231], v[22:25]
	v_mfma_f32_16x16x32_bf16 v[18:21], v[204:207], v[228:231], v[18:21]
	v_mfma_f32_16x16x32_bf16 v[6:9], v[178:181], v[236:239], v[6:9]
	v_mfma_f32_16x16x32_bf16 v[2:5], v[204:207], v[236:239], v[2:5]
	s_setprio 0
	s_setprio 1
	v_mfma_f32_16x16x32_bf16 v[54:57], v[182:185], v[216:219], v[54:57]
	v_mfma_f32_16x16x32_bf16 v[50:53], v[208:211], v[216:219], v[50:53]
	v_mfma_f32_16x16x32_bf16 v[38:41], v[182:185], v[224:227], v[38:41]
	v_mfma_f32_16x16x32_bf16 v[34:37], v[208:211], v[224:227], v[34:37]
	v_mfma_f32_16x16x32_bf16 v[22:25], v[182:185], v[232:235], v[22:25]
	v_mfma_f32_16x16x32_bf16 v[18:21], v[208:211], v[232:235], v[18:21]
	v_mfma_f32_16x16x32_bf16 v[6:9], v[182:185], v[240:243], v[6:9]
	v_mfma_f32_16x16x32_bf16 v[2:5], v[208:211], v[240:243], v[2:5]
	s_setprio 0
	s_barrier
	s_add_i32 s46, s46, 2
	s_add_u32 s60, s60, 0x100
	s_addc_u32 s73, s73, 0
	s_cmp_gt_u32 s46, 21
	s_mov_b64 s[36:37], s[42:43]
	s_cbranch_scc0 .LBB0_160
	s_and_b64 vcc, exec, s[10:11]
	s_cbranch_vccz .LBB0_163
	s_barrier

; #define PG8_STAGE(bufoff, gbase, voff) do { _Pragma("unroll") for (int _i = 0; _i < 2; ++_i) \
;         __builtin_amdgcn_global_load_lds((const unsigned*)((const char*)(gbase) + (voff)[_i]), (PG8_LAS unsigned*)(lds + (bufoff) + ldsw + _i * 8192), 16, 0, 0); } while (0)
; #define PG8_LDA(dst, b, h) do { _Pragma("unroll") for (int m = 0; m < 4; ++m) _Pragma("unroll") for (int k = 0; k < 2; ++k) dst[m][k] = *(const PG8_LAS bf16x8*)(lds + PG8_SA(b, h) + aoff + m * 2048 + k * 1024); } while (0)
; #define PG8_LDB(dst, b, h) do { _Pragma("unroll") for (int n = 0; n < 2; ++n) _Pragma("unroll") for (int k = 0; k < 2; ++k) dst[n][k] = *(const PG8_LAS bf16x8*)(lds + PG8_SB(b, h) + boff + n * 2048 + k * 1024); } while (0)
; #define PG8_WAIT_V(n) asm volatile("s_waitcnt vmcnt(" #n ")" ::: "memory")
; #define PG8_WAIT_L(n) asm volatile("s_waitcnt lgkmcnt(" #n ")" ::: "memory")
; #define PG8_BAR __builtin_amdgcn_s_barrier()
; #define PG8_SCHED __builtin_amdgcn_sched_barrier(0)
; template <class Epi, class Sched, bool ALIGN_EPI = false, bool SP2 = false>
; __device__ __forceinline__ void gemm_phase(PG8_LAS unsigned char* lds, const Gemm g, const Sched& S, const Epi& E) {
;     ...
;         const char* nA = has_next ? (const char*)g.A + (size_t)nxt.pm * tstep : cA; const char* nB = has_next ? (const char*)g.Bt + (size_t)nxt.pn * tstep : cB;
;         for (int t = 0; t < nt; t += 2) {
;             const bool last = (t == nt - 2);
;             const char* a1 = cA + (size_t)(t + 1) * kstep;
;             const char* a2 = last ? nA : cA + (size_t)(t + 2) * kstep; const char* b2 = last ? nB : cB + (size_t)(t + 2) * kstep;
;             const char* a3 = a2 + kstep; const char* b3 = b2 + kstep;
;             if (last && has_next) S.a_ready(nxt);
;             if constexpr (SP2) {
;             PG8_LDB(B0, 0, 0); PG8_LDB(B1, 0, 1); PG8_SCHED; PG8_LDA(At, 0, 0); PG8_STAGE(PG8_SA(1, 1), a1 + hstep, voffA);
;             PG8_WAIT_V(8); PG8_WAIT_L(0); PG8_BAR; PG8_MMA(0, 0, At, B0); PG8_MMA(0, 1, At, B1); PG8_BAR; PG8_SCHED;
;             PG8_LDA(At, 0, 1); PG8_STAGE(PG8_SB(0, 0), b2, voffB); PG8_STAGE(PG8_SB(0, 1), b2 + hstep, voffB); PG8_STAGE(PG8_SA(0, 0), a2, voffA);
;             PG8_WAIT_V(8); PG8_WAIT_L(0); PG8_BAR; PG8_MMA(1, 0, At, B0); PG8_MMA(1, 1, At, B1); PG8_BAR; PG8_SCHED;
.LBB0_281:
	s_add_u32 s18, s36, 0xfff80080
	s_addc_u32 s19, s37, -1
	s_add_i32 s73, 0, 0x10000
	s_cmp_eq_u32 s67, 28
	s_cselect_b32 s43, s9, s19
	s_cselect_b32 s42, s59, s18
	v_add_u32_e32 v163, s73, v160
	s_cselect_b32 s19, s7, s63
	s_cselect_b32 s18, s60, s62
	s_add_i32 s76, 0, 0x14000
	ds_read_b128 v[156:159], v163
	ds_read_b128 v[164:167], v163 offset:1024
	ds_read_b128 v[168:171], v163 offset:2048
	ds_read_b128 v[172:175], v163 offset:3072
	v_add_u32_e32 v163, s76, v160
	ds_read_b128 v[176:179], v163
	ds_read_b128 v[180:183], v163 offset:1024
	ds_read_b128 v[184:187], v163 offset:2048
	ds_read_b128 v[204:207], v163 offset:3072
	v_lshl_add_u64 v[240:241], s[36:37], 0, v[152:153]
	s_add_i32 m0, s30, 0xc000
	ds_read_b128 v[208:211], v162
	ds_read_b128 v[212:215], v162 offset:1024
	ds_read_b128 v[216:219], v162 offset:2048
	ds_read_b128 v[220:223], v162 offset:3072
	ds_read_b128 v[224:227], v162 offset:4096
	ds_read_b128 v[228:231], v162 offset:5120
	ds_read_b128 v[232:235], v162 offset:6144
	ds_read_b128 v[236:239], v162 offset:7168
	global_load_lds_dwordx4 v[240:241], off
	v_lshl_add_u64 v[240:241], s[36:37], 0, v[154:155]
	s_add_i32 m0, s30, 0xe000
	s_nop 0
	global_load_lds_dwordx4 v[240:241], off
	s_nop 0
	s_nop 0
	s_waitcnt vmcnt(8)
	s_waitcnt lgkmcnt(0)
	s_setprio 1
	s_barrier
	v_mfma_f32_16x16x32_bf16 v[126:129], v[156:159], v[208:211], v[126:129]
	v_mfma_f32_16x16x32_bf16 v[122:125], v[168:171], v[208:211], v[122:125]
	v_mfma_f32_16x16x32_bf16 v[110:113], v[156:159], v[216:219], v[110:113]
	v_mfma_f32_16x16x32_bf16 v[106:109], v[168:171], v[216:219], v[106:109]
	v_mfma_f32_16x16x32_bf16 v[94:97], v[156:159], v[224:227], v[94:97]
	v_mfma_f32_16x16x32_bf16 v[90:93], v[168:171], v[224:227], v[90:93]
	v_mfma_f32_16x16x32_bf16 v[78:81], v[156:159], v[232:235], v[78:81]
	v_mfma_f32_16x16x32_bf16 v[74:77], v[168:171], v[232:235], v[74:77]
	s_setprio 0
	s_setprio 1
	v_mfma_f32_16x16x32_bf16 v[126:129], v[164:167], v[212:215], v[126:129]
	v_mfma_f32_16x16x32_bf16 v[122:125], v[172:175], v[212:215], v[122:125]
	v_mfma_f32_16x16x32_bf16 v[110:113], v[164:167], v[220:223], v[110:113]
	v_mfma_f32_16x16x32_bf16 v[106:109], v[172:175], v[220:223], v[106:109]
	v_mfma_f32_16x16x32_bf16 v[94:97], v[164:167], v[228:231], v[94:97]
	v_mfma_f32_16x16x32_bf16 v[90:93], v[172:175], v[228:231], v[90:93]
	v_mfma_f32_16x16x32_bf16 v[78:81], v[164:167], v[236:239], v[78:81]
	v_mfma_f32_16x16x32_bf16 v[74:77], v[172:175], v[236:239], v[74:77]
	s_setprio 0
	s_setprio 1
	v_mfma_f32_16x16x32_bf16 v[118:121], v[176:179], v[208:211], v[118:121]
	v_mfma_f32_16x16x32_bf16 v[114:117], v[184:187], v[208:211], v[114:117]
	v_mfma_f32_16x16x32_bf16 v[102:105], v[176:179], v[216:219], v[102:105]
	v_mfma_f32_16x16x32_bf16 v[98:101], v[184:187], v[216:219], v[98:101]
	v_mfma_f32_16x16x32_bf16 v[86:89], v[176:179], v[224:227], v[86:89]
	v_mfma_f32_16x16x32_bf16 v[82:85], v[184:187], v[224:227], v[82:85]
	v_mfma_f32_16x16x32_bf16 v[70:73], v[176:179], v[232:235], v[70:73]
	v_mfma_f32_16x16x32_bf16 v[66:69], v[184:187], v[232:235], v[66:69]
	s_setprio 0
	s_setprio 1
	v_mfma_f32_16x16x32_bf16 v[118:121], v[180:183], v[212:215], v[118:121]
	v_mfma_f32_16x16x32_bf16 v[114:117], v[204:207], v[212:215], v[114:117]
	v_mfma_f32_16x16x32_bf16 v[102:105], v[180:183], v[220:223], v[102:105]
	v_mfma_f32_16x16x32_bf16 v[98:101], v[204:207], v[220:223], v[98:101]
	v_mfma_f32_16x16x32_bf16 v[86:89], v[180:183], v[228:231], v[86:89]
	v_mfma_f32_16x16x32_bf16 v[82:85], v[204:207], v[228:231], v[82:85]
	v_mfma_f32_16x16x32_bf16 v[70:73], v[180:183], v[236:239], v[70:73]
	v_mfma_f32_16x16x32_bf16 v[66:69], v[204:207], v[236:239], v[66:69]
	s_setprio 0
	s_barrier
	s_add_i32 s73, s73, s28
	v_lshl_add_u64 v[240:241], s[18:19], 0, v[146:147]
	s_mov_b32 m0, s73
	ds_read_b128 v[208:211], v162 offset:16384
	ds_read_b128 v[212:215], v162 offset:17408
	ds_read_b128 v[216:219], v162 offset:18432
	ds_read_b128 v[220:223], v162 offset:19456
	ds_read_b128 v[224:227], v162 offset:20480
	ds_read_b128 v[228:231], v162 offset:21504
	ds_read_b128 v[232:235], v162 offset:22528
	ds_read_b128 v[236:239], v162 offset:23552
	global_load_lds_dwordx4 v[240:241], off
	s_add_i32 m0, s73, 0x2000
	s_add_u32 s78, s18, 0x80000
	v_lshl_add_u64 v[242:243], s[18:19], 0, v[142:143]
	s_addc_u32 s79, s19, 0
	s_add_i32 s73, s76, s28
	global_load_lds_dwordx4 v[242:243], off
	v_lshl_add_u64 v[244:245], s[78:79], 0, v[146:147]
	s_mov_b32 m0, s73
	v_lshl_add_u64 v[246:247], s[42:43], 0, v[144:145]
	global_load_lds_dwordx4 v[244:245], off
	v_lshl_add_u64 v[244:245], s[78:79], 0, v[142:143]
	s_add_i32 m0, s73, 0x2000
	s_nop 0
	global_load_lds_dwordx4 v[244:245], off
	v_lshl_add_u64 v[244:245], s[42:43], 0, v[148:149]
	s_mov_b32 m0, s30
	s_nop 0
	global_load_lds_dwordx4 v[244:245], off
	s_mov_b32 m0, s34
	s_nop 0
	global_load_lds_dwordx4 v[246:247], off
	s_waitcnt vmcnt(8)
	s_waitcnt lgkmcnt(0)
	s_setprio 1
	s_barrier
; #define PG8_STAGE(bufoff, gbase, voff) do { _Pragma("unroll") for (int _i = 0; _i < 2; ++_i) \
;         __builtin_amdgcn_global_load_lds((const unsigned*)((const char*)(gbase) + (voff)[_i]), (PG8_LAS unsigned*)(lds + (bufoff) + ldsw + _i * 8192), 16, 0, 0); } while (0)
; #define PG8_LDA(dst, b, h) do { _Pragma("unroll") for (int m = 0; m < 4; ++m) _Pragma("unroll") for (int k = 0; k < 2; ++k) dst[m][k] = *(const PG8_LAS bf16x8*)(lds + PG8_SA(b, h) + aoff + m * 2048 + k * 1024); } while (0)
; #define PG8_LDB(dst, b, h) do { _Pragma("unroll") for (int n = 0; n < 2; ++n) _Pragma("unroll") for (int k = 0; k < 2; ++k) dst[n][k] = *(const PG8_LAS bf16x8*)(lds + PG8_SB(b, h) + boff + n * 2048 + k * 1024); } while (0)
; #define PG8_MMA(ai, bj, At, Bt) do { __builtin_amdgcn_s_setprio(1); _Pragma("unroll") for (int m = 0; m < 4; ++m) _Pragma("unroll") for (int n = 0; n < 2; ++n) _Pragma("unroll") for (int k = 0; k < 2; ++k) \
;         acc[ai][bj][m][n] = __builtin_amdgcn_mfma_f32_16x16x32_bf16(Bt[n][k], At[m][k], acc[ai][bj][m][n], 0, 0, 0); __builtin_amdgcn_s_setprio(0); } while (0)
; #define PG8_WAIT_V(n) asm volatile("s_waitcnt vmcnt(" #n ")" ::: "memory")
; #define PG8_WAIT_L(n) asm volatile("s_waitcnt lgkmcnt(" #n ")" ::: "memory")
; #define PG8_BAR __builtin_amdgcn_s_barrier()
; #define PG8_SCHED __builtin_amdgcn_sched_barrier(0)
; template <class Epi, class Sched, bool ALIGN_EPI = false, bool SP2 = false>
; __device__ __forceinline__ void gemm_phase(PG8_LAS unsigned char* lds, const Gemm g, const Sched& S, const Epi& E) {
;     ...
;             PG8_WAIT_V(8); PG8_WAIT_L(0); PG8_BAR; PG8_MMA(1, 0, At, B0); PG8_MMA(1, 1, At, B1); PG8_BAR; PG8_SCHED;
;             PG8_LDB(B0, 1, 0); PG8_LDB(B1, 1, 1); PG8_SCHED; PG8_LDA(At, 1, 0); PG8_STAGE(PG8_SA(0, 1), a2 + hstep, voffA);
;             PG8_WAIT_V(8); PG8_WAIT_L(0); PG8_BAR; PG8_MMA(0, 0, At, B0); PG8_MMA(0, 1, At, B1); PG8_BAR; PG8_SCHED;
	v_mfma_f32_16x16x32_bf16 v[62:65], v[156:159], v[208:211], v[62:65]
	v_mfma_f32_16x16x32_bf16 v[58:61], v[168:171], v[208:211], v[58:61]
	v_mfma_f32_16x16x32_bf16 v[46:49], v[156:159], v[216:219], v[46:49]
	v_mfma_f32_16x16x32_bf16 v[42:45], v[168:171], v[216:219], v[42:45]
	v_mfma_f32_16x16x32_bf16 v[30:33], v[156:159], v[224:227], v[30:33]
	v_mfma_f32_16x16x32_bf16 v[26:29], v[168:171], v[224:227], v[26:29]
	v_mfma_f32_16x16x32_bf16 v[14:17], v[156:159], v[232:235], v[14:17]
	v_mfma_f32_16x16x32_bf16 v[10:13], v[168:171], v[232:235], v[10:13]
	s_setprio 0
	s_setprio 1
	v_mfma_f32_16x16x32_bf16 v[62:65], v[164:167], v[212:215], v[62:65]
	v_mfma_f32_16x16x32_bf16 v[58:61], v[172:175], v[212:215], v[58:61]
	v_mfma_f32_16x16x32_bf16 v[46:49], v[164:167], v[220:223], v[46:49]
	v_mfma_f32_16x16x32_bf16 v[42:45], v[172:175], v[220:223], v[42:45]
	v_mfma_f32_16x16x32_bf16 v[30:33], v[164:167], v[228:231], v[30:33]
	v_mfma_f32_16x16x32_bf16 v[26:29], v[172:175], v[228:231], v[26:29]
	v_mfma_f32_16x16x32_bf16 v[14:17], v[164:167], v[236:239], v[14:17]
	v_mfma_f32_16x16x32_bf16 v[10:13], v[172:175], v[236:239], v[10:13]
	s_setprio 0
	s_setprio 1
	v_mfma_f32_16x16x32_bf16 v[54:57], v[176:179], v[208:211], v[54:57]
	v_mfma_f32_16x16x32_bf16 v[50:53], v[184:187], v[208:211], v[50:53]
	v_mfma_f32_16x16x32_bf16 v[38:41], v[176:179], v[216:219], v[38:41]
	v_mfma_f32_16x16x32_bf16 v[34:37], v[184:187], v[216:219], v[34:37]
	v_mfma_f32_16x16x32_bf16 v[22:25], v[176:179], v[224:227], v[22:25]
	v_mfma_f32_16x16x32_bf16 v[18:21], v[184:187], v[224:227], v[18:21]
	v_mfma_f32_16x16x32_bf16 v[6:9], v[176:179], v[232:235], v[6:9]
	v_mfma_f32_16x16x32_bf16 v[2:5], v[184:187], v[232:235], v[2:5]
	s_setprio 0
	s_setprio 1
	v_mfma_f32_16x16x32_bf16 v[54:57], v[180:183], v[212:215], v[54:57]
	v_mfma_f32_16x16x32_bf16 v[50:53], v[204:207], v[212:215], v[50:53]
	v_mfma_f32_16x16x32_bf16 v[38:41], v[180:183], v[220:223], v[38:41]
	v_mfma_f32_16x16x32_bf16 v[34:37], v[204:207], v[220:223], v[34:37]
	v_mfma_f32_16x16x32_bf16 v[22:25], v[180:183], v[228:231], v[22:25]
	v_mfma_f32_16x16x32_bf16 v[18:21], v[204:207], v[228:231], v[18:21]
	v_mfma_f32_16x16x32_bf16 v[6:9], v[180:183], v[236:239], v[6:9]
	v_mfma_f32_16x16x32_bf16 v[2:5], v[204:207], v[236:239], v[2:5]
	s_setprio 0
	s_barrier
	s_add_i32 s73, 0, 0x18000
	v_add_u32_e32 v163, s73, v160
	s_add_i32 s76, 0, 0x1c000
	ds_read_b128 v[156:159], v163
	ds_read_b128 v[164:167], v163 offset:1024
	ds_read_b128 v[168:171], v163 offset:2048
	ds_read_b128 v[172:175], v163 offset:3072
	v_add_u32_e32 v163, s76, v160
	ds_read_b128 v[176:179], v163
	ds_read_b128 v[180:183], v163 offset:1024
	ds_read_b128 v[184:187], v163 offset:2048
	ds_read_b128 v[204:207], v163 offset:3072
	s_add_u32 s42, s42, 0x80000
	s_addc_u32 s43, s43, 0
	s_mov_b32 m0, s44
	v_lshl_add_u64 v[248:249], s[42:43], 0, v[148:149]
	ds_read_b128 v[208:211], v162 offset:32768
	ds_read_b128 v[212:215], v162 offset:33792
	ds_read_b128 v[216:219], v162 offset:34816
	ds_read_b128 v[220:223], v162 offset:35840
	ds_read_b128 v[224:227], v162 offset:36864
	ds_read_b128 v[228:231], v162 offset:37888
	ds_read_b128 v[232:235], v162 offset:38912
	ds_read_b128 v[236:239], v162 offset:39936
	global_load_lds_dwordx4 v[248:249], off
	v_lshl_add_u64 v[248:249], s[42:43], 0, v[144:145]
	s_mov_b32 m0, s45
	s_nop 0
	global_load_lds_dwordx4 v[248:249], off
	s_waitcnt vmcnt(8)
	s_waitcnt lgkmcnt(0)
	s_setprio 1
	s_barrier
	v_mfma_f32_16x16x32_bf16 v[126:129], v[156:159], v[208:211], v[126:129]
	v_mfma_f32_16x16x32_bf16 v[122:125], v[168:171], v[208:211], v[122:125]
	v_mfma_f32_16x16x32_bf16 v[110:113], v[156:159], v[216:219], v[110:113]
	v_mfma_f32_16x16x32_bf16 v[106:109], v[168:171], v[216:219], v[106:109]
	v_mfma_f32_16x16x32_bf16 v[94:97], v[156:159], v[224:227], v[94:97]
	v_mfma_f32_16x16x32_bf16 v[90:93], v[168:171], v[224:227], v[90:93]
	v_mfma_f32_16x16x32_bf16 v[78:81], v[156:159], v[232:235], v[78:81]
	v_mfma_f32_16x16x32_bf16 v[74:77], v[168:171], v[232:235], v[74:77]
	s_setprio 0
	s_setprio 1
	v_mfma_f32_16x16x32_bf16 v[126:129], v[164:167], v[212:215], v[126:129]
	v_mfma_f32_16x16x32_bf16 v[122:125], v[172:175], v[212:215], v[122:125]
	v_mfma_f32_16x16x32_bf16 v[110:113], v[164:167], v[220:223], v[110:113]
	v_mfma_f32_16x16x32_bf16 v[106:109], v[172:175], v[220:223], v[106:109]
	v_mfma_f32_16x16x32_bf16 v[94:97], v[164:167], v[228:231], v[94:97]
	v_mfma_f32_16x16x32_bf16 v[90:93], v[172:175], v[228:231], v[90:93]
	v_mfma_f32_16x16x32_bf16 v[78:81], v[164:167], v[236:239], v[78:81]
	v_mfma_f32_16x16x32_bf16 v[74:77], v[172:175], v[236:239], v[74:77]
	s_setprio 0
	s_setprio 1
	v_mfma_f32_16x16x32_bf16 v[118:121], v[176:179], v[208:211], v[118:121]
	v_mfma_f32_16x16x32_bf16 v[114:117], v[184:187], v[208:211], v[114:117]
	v_mfma_f32_16x16x32_bf16 v[102:105], v[176:179], v[216:219], v[102:105]
	v_mfma_f32_16x16x32_bf16 v[98:101], v[184:187], v[216:219], v[98:101]
	v_mfma_f32_16x16x32_bf16 v[86:89], v[176:179], v[224:227], v[86:89]
	v_mfma_f32_16x16x32_bf16 v[82:85], v[184:187], v[224:227], v[82:85]
	v_mfma_f32_16x16x32_bf16 v[70:73], v[176:179], v[232:235], v[70:73]
	v_mfma_f32_16x16x32_bf16 v[66:69], v[184:187], v[232:235], v[66:69]
	s_setprio 0
	s_setprio 1
	v_mfma_f32_16x16x32_bf16 v[118:121], v[180:183], v[212:215], v[118:121]
	v_mfma_f32_16x16x32_bf16 v[114:117], v[204:207], v[212:215], v[114:117]
	v_mfma_f32_16x16x32_bf16 v[102:105], v[180:183], v[220:223], v[102:105]
	v_mfma_f32_16x16x32_bf16 v[98:101], v[204:207], v[220:223], v[98:101]
	v_mfma_f32_16x16x32_bf16 v[86:89], v[180:183], v[228:231], v[86:89]
	v_mfma_f32_16x16x32_bf16 v[82:85], v[204:207], v[228:231], v[82:85]
	v_mfma_f32_16x16x32_bf16 v[70:73], v[180:183], v[236:239], v[70:73]
	v_mfma_f32_16x16x32_bf16 v[66:69], v[204:207], v[236:239], v[66:69]
	s_setprio 0
	s_barrier
; #define PG8_STAGE(bufoff, gbase, voff) do { _Pragma("unroll") for (int _i = 0; _i < 2; ++_i) \
;         __builtin_amdgcn_global_load_lds((const unsigned*)((const char*)(gbase) + (voff)[_i]), (PG8_LAS unsigned*)(lds + (bufoff) + ldsw + _i * 8192), 16, 0, 0); } while (0)
; #define PG8_LDA(dst, b, h) do { _Pragma("unroll") for (int m = 0; m < 4; ++m) _Pragma("unroll") for (int k = 0; k < 2; ++k) dst[m][k] = *(const PG8_LAS bf16x8*)(lds + PG8_SA(b, h) + aoff + m * 2048 + k * 1024); } while (0)
; #define PG8_MMA(ai, bj, At, Bt) do { __builtin_amdgcn_s_setprio(1); _Pragma("unroll") for (int m = 0; m < 4; ++m) _Pragma("unroll") for (int n = 0; n < 2; ++n) _Pragma("unroll") for (int k = 0; k < 2; ++k) \
;         acc[ai][bj][m][n] = __builtin_amdgcn_mfma_f32_16x16x32_bf16(Bt[n][k], At[m][k], acc[ai][bj][m][n], 0, 0, 0); __builtin_amdgcn_s_setprio(0); } while (0)
; #define PG8_WAIT_V(n) asm volatile("s_waitcnt vmcnt(" #n ")" ::: "memory")
; #define PG8_WAIT_L(n) asm volatile("s_waitcnt lgkmcnt(" #n ")" ::: "memory")
; #define PG8_BAR __builtin_amdgcn_s_barrier()
; #define PG8_SCHED __builtin_amdgcn_sched_barrier(0)
;     __device__ __forceinline__ void operator()(const f32x4 (&acc)[2][2][4][2], const Unit& u, int wr, int wc, int fr, int fq) const {
;     ...
;         if (u.pn >= 30) {
; template <class Epi, class Sched, bool ALIGN_EPI = false, bool SP2 = false>
; __device__ __forceinline__ void gemm_phase(PG8_LAS unsigned char* lds, const Gemm g, const Sched& S, const Epi& E) {
;     ...
;             PG8_LDA(At, 1, 1); PG8_STAGE(PG8_SB(1, 0), b3, voffB); PG8_STAGE(PG8_SB(1, 1), b3 + hstep, voffB); PG8_STAGE(PG8_SA(1, 0), a3, voffA);
;             PG8_WAIT_V(8); PG8_WAIT_L(0); PG8_BAR; PG8_MMA(1, 0, At, B0); PG8_MMA(1, 1, At, B1); PG8_BAR; PG8_SCHED;
	s_add_i32 s42, s73, s28
	v_lshl_add_u64 v[240:241], v[240:241], 0, s[68:69]
	s_mov_b32 m0, s42
	ds_read_b128 v[208:211], v162 offset:49152
	ds_read_b128 v[212:215], v162 offset:50176
	ds_read_b128 v[216:219], v162 offset:51200
	ds_read_b128 v[220:223], v162 offset:52224
	ds_read_b128 v[224:227], v162 offset:53248
	ds_read_b128 v[228:231], v162 offset:54272
	ds_read_b128 v[232:235], v162 offset:55296
	ds_read_b128 v[236:239], v162 offset:56320
	global_load_lds_dwordx4 v[240:241], off
	s_add_i32 m0, s42, 0x2000
	s_add_u32 s18, s18, 0x80080
	v_lshl_add_u64 v[240:241], v[242:243], 0, s[68:69]
	s_addc_u32 s19, s19, 0
	s_add_i32 s42, s76, s28
	global_load_lds_dwordx4 v[240:241], off
	v_lshl_add_u64 v[240:241], s[18:19], 0, v[146:147]
	s_mov_b32 m0, s42
	s_nop 0
	global_load_lds_dwordx4 v[240:241], off
	v_lshl_add_u64 v[240:241], s[18:19], 0, v[142:143]
	s_add_i32 m0, s42, 0x2000
	s_nop 0
	global_load_lds_dwordx4 v[240:241], off
	v_lshl_add_u64 v[240:241], v[244:245], 0, s[68:69]
	s_mov_b32 m0, s46
	s_nop 0
	global_load_lds_dwordx4 v[240:241], off
	v_lshl_add_u64 v[240:241], v[246:247], 0, s[68:69]
	s_mov_b32 m0, s47
	s_nop 0
	global_load_lds_dwordx4 v[240:241], off
	s_nop 0
	s_waitcnt vmcnt(8)
	s_waitcnt lgkmcnt(0)
	s_setprio 1
	s_barrier
	v_mfma_f32_16x16x32_bf16 v[62:65], v[156:159], v[208:211], v[62:65]
	v_mfma_f32_16x16x32_bf16 v[58:61], v[168:171], v[208:211], v[58:61]
	v_mfma_f32_16x16x32_bf16 v[46:49], v[156:159], v[216:219], v[46:49]
	v_mfma_f32_16x16x32_bf16 v[42:45], v[168:171], v[216:219], v[42:45]
	v_mfma_f32_16x16x32_bf16 v[30:33], v[156:159], v[224:227], v[30:33]
	v_mfma_f32_16x16x32_bf16 v[26:29], v[168:171], v[224:227], v[26:29]
	v_mfma_f32_16x16x32_bf16 v[14:17], v[156:159], v[232:235], v[14:17]
	v_mfma_f32_16x16x32_bf16 v[10:13], v[168:171], v[232:235], v[10:13]
	s_setprio 0
	s_setprio 1
	v_mfma_f32_16x16x32_bf16 v[62:65], v[164:167], v[212:215], v[62:65]
	v_mfma_f32_16x16x32_bf16 v[58:61], v[172:175], v[212:215], v[58:61]
	v_mfma_f32_16x16x32_bf16 v[46:49], v[164:167], v[220:223], v[46:49]
	v_mfma_f32_16x16x32_bf16 v[42:45], v[172:175], v[220:223], v[42:45]
	v_mfma_f32_16x16x32_bf16 v[30:33], v[164:167], v[228:231], v[30:33]
	v_mfma_f32_16x16x32_bf16 v[26:29], v[172:175], v[228:231], v[26:29]
	v_mfma_f32_16x16x32_bf16 v[14:17], v[164:167], v[236:239], v[14:17]
	v_mfma_f32_16x16x32_bf16 v[10:13], v[172:175], v[236:239], v[10:13]
	s_setprio 0
	s_setprio 1
	v_mfma_f32_16x16x32_bf16 v[54:57], v[176:179], v[208:211], v[54:57]
	v_mfma_f32_16x16x32_bf16 v[50:53], v[184:187], v[208:211], v[50:53]
	v_mfma_f32_16x16x32_bf16 v[38:41], v[176:179], v[216:219], v[38:41]
	v_mfma_f32_16x16x32_bf16 v[34:37], v[184:187], v[216:219], v[34:37]
	v_mfma_f32_16x16x32_bf16 v[22:25], v[176:179], v[224:227], v[22:25]
	v_mfma_f32_16x16x32_bf16 v[18:21], v[184:187], v[224:227], v[18:21]
	v_mfma_f32_16x16x32_bf16 v[6:9], v[176:179], v[232:235], v[6:9]
	v_mfma_f32_16x16x32_bf16 v[2:5], v[184:187], v[232:235], v[2:5]
	s_setprio 0
	s_setprio 1
	v_mfma_f32_16x16x32_bf16 v[54:57], v[180:183], v[212:215], v[54:57]
	v_mfma_f32_16x16x32_bf16 v[50:53], v[204:207], v[212:215], v[50:53]
	v_mfma_f32_16x16x32_bf16 v[38:41], v[180:183], v[220:223], v[38:41]
	v_mfma_f32_16x16x32_bf16 v[34:37], v[204:207], v[220:223], v[34:37]
	v_mfma_f32_16x16x32_bf16 v[22:25], v[180:183], v[228:231], v[22:25]
	v_mfma_f32_16x16x32_bf16 v[18:21], v[204:207], v[228:231], v[18:21]
	v_mfma_f32_16x16x32_bf16 v[6:9], v[180:183], v[236:239], v[6:9]
	v_mfma_f32_16x16x32_bf16 v[2:5], v[204:207], v[236:239], v[2:5]
	s_setprio 0
	s_barrier
	s_add_i32 s67, s67, 2
	s_add_u32 s36, s36, 0x100
	s_addc_u32 s37, s37, 0
	s_add_u32 s62, s62, 0x100
	s_addc_u32 s63, s63, 0
	s_cmp_gt_u32 s67, 29
	s_cbranch_scc0 .LBB0_281
	s_and_b64 vcc, exec, s[4:5]
	s_cbranch_vccnz .LBB0_286
	s_cmp_lt_i32 s57, 30
	s_mov_b64 s[18:19], -1
	s_cbranch_scc1 .LBB0_287
